# P7 idle-workgroup weight-transpose load loops unrolled (32 loads in flight) on top of P0 rebalance/unroll and P3 epilogue
# baseline (speedup 1.0000x reference)
; __device__ __forceinline__ void transpose_item(const float* W, int K, int N, bf16_t* WT, int dst0, int src0, int mode, int nblk, LAS float* scr, int item, int lane) {
;     ...
;     const int sc = srccol(mode, n0 + (lane & 31), src0);
; #pragma unroll 8
;     for (int i = 0; i < 32; ++i) { const int kk = 2 * i + (lane >> 5); scr[kk * 33 + (lane & 31)] = __builtin_nontemporal_load(W + (size_t)(k0 + kk) * N + sc); }
.LBB0_306:
	v_add_u32_e32 v17, s7, v0
	v_mad_i64_i32 v[18:19], s[22:23], v17, s26, v[14:15]
	v_add_u32_e32 v20, 2, v17
	v_add_u32_e32 v22, 4, v17
	v_add_u32_e32 v24, 6, v17
	v_add_u32_e32 v26, 8, v17
	v_add_u32_e32 v28, 10, v17
	v_add_u32_e32 v47, 12, v17
	v_add_u32_e32 v17, 14, v17
	v_mad_i64_i32 v[20:21], s[22:23], v20, s26, v[14:15]
	v_mad_i64_i32 v[22:23], s[22:23], v22, s26, v[14:15]
	v_mad_i64_i32 v[24:25], s[22:23], v24, s26, v[14:15]
	v_mad_i64_i32 v[26:27], s[22:23], v26, s26, v[14:15]
	v_mad_i64_i32 v[28:29], s[22:23], v28, s26, v[14:15]
	v_mad_i64_i32 v[48:49], s[22:23], v47, s26, v[14:15]
	v_mad_i64_i32 v[50:51], s[22:23], v17, s26, v[14:15]
	global_load_dword v64, v[18:19], off nt
	global_load_dword v65, v[20:21], off nt
	global_load_dword v66, v[22:23], off nt
	global_load_dword v67, v[24:25], off nt
	global_load_dword v68, v[26:27], off nt
	global_load_dword v69, v[28:29], off nt
	global_load_dword v70, v[48:49], off nt
	global_load_dword v71, v[50:51], off nt
	s_add_i32 s7, s7, 16
	v_add_u32_e32 v17, s7, v0
	v_mad_i64_i32 v[18:19], s[22:23], v17, s26, v[14:15]
	v_add_u32_e32 v20, 2, v17
	v_add_u32_e32 v22, 4, v17
	v_add_u32_e32 v24, 6, v17
	v_add_u32_e32 v26, 8, v17
	v_add_u32_e32 v28, 10, v17
	v_add_u32_e32 v47, 12, v17
	v_add_u32_e32 v17, 14, v17
	v_mad_i64_i32 v[20:21], s[22:23], v20, s26, v[14:15]
	v_mad_i64_i32 v[22:23], s[22:23], v22, s26, v[14:15]
	v_mad_i64_i32 v[24:25], s[22:23], v24, s26, v[14:15]
	v_mad_i64_i32 v[26:27], s[22:23], v26, s26, v[14:15]
	v_mad_i64_i32 v[28:29], s[22:23], v28, s26, v[14:15]
	v_mad_i64_i32 v[48:49], s[22:23], v47, s26, v[14:15]
	v_mad_i64_i32 v[50:51], s[22:23], v17, s26, v[14:15]
	global_load_dword v72, v[18:19], off nt
	global_load_dword v73, v[20:21], off nt
	global_load_dword v74, v[22:23], off nt
	global_load_dword v75, v[24:25], off nt
	global_load_dword v76, v[26:27], off nt
	global_load_dword v77, v[28:29], off nt
	global_load_dword v78, v[48:49], off nt
	global_load_dword v79, v[50:51], off nt
	s_add_i32 s7, s7, 16
	v_add_u32_e32 v17, s7, v0
	v_mad_i64_i32 v[18:19], s[22:23], v17, s26, v[14:15]
	v_add_u32_e32 v20, 2, v17
	v_add_u32_e32 v22, 4, v17
	v_add_u32_e32 v24, 6, v17
	v_add_u32_e32 v26, 8, v17
	v_add_u32_e32 v28, 10, v17
	v_add_u32_e32 v47, 12, v17
	v_add_u32_e32 v17, 14, v17
	v_mad_i64_i32 v[20:21], s[22:23], v20, s26, v[14:15]
	v_mad_i64_i32 v[22:23], s[22:23], v22, s26, v[14:15]
	v_mad_i64_i32 v[24:25], s[22:23], v24, s26, v[14:15]
	v_mad_i64_i32 v[26:27], s[22:23], v26, s26, v[14:15]
	v_mad_i64_i32 v[28:29], s[22:23], v28, s26, v[14:15]
	v_mad_i64_i32 v[48:49], s[22:23], v47, s26, v[14:15]
	v_mad_i64_i32 v[50:51], s[22:23], v17, s26, v[14:15]
	global_load_dword v80, v[18:19], off nt
	global_load_dword v81, v[20:21], off nt
	global_load_dword v82, v[22:23], off nt
	global_load_dword v83, v[24:25], off nt
	global_load_dword v84, v[26:27], off nt
	global_load_dword v85, v[28:29], off nt
	global_load_dword v86, v[48:49], off nt
	global_load_dword v87, v[50:51], off nt
	s_add_i32 s7, s7, 16
	v_add_u32_e32 v17, s7, v0
	v_mad_i64_i32 v[18:19], s[22:23], v17, s26, v[14:15]
	v_add_u32_e32 v20, 2, v17
	v_add_u32_e32 v22, 4, v17
	v_add_u32_e32 v24, 6, v17
	v_add_u32_e32 v26, 8, v17
	v_add_u32_e32 v28, 10, v17
	v_add_u32_e32 v47, 12, v17
	v_add_u32_e32 v17, 14, v17
	v_mad_i64_i32 v[20:21], s[22:23], v20, s26, v[14:15]
	v_mad_i64_i32 v[22:23], s[22:23], v22, s26, v[14:15]
	v_mad_i64_i32 v[24:25], s[22:23], v24, s26, v[14:15]
	v_mad_i64_i32 v[26:27], s[22:23], v26, s26, v[14:15]
	v_mad_i64_i32 v[28:29], s[22:23], v28, s26, v[14:15]
	v_mad_i64_i32 v[48:49], s[22:23], v47, s26, v[14:15]
	v_mad_i64_i32 v[50:51], s[22:23], v17, s26, v[14:15]
	global_load_dword v88, v[18:19], off nt
	global_load_dword v89, v[20:21], off nt
	global_load_dword v90, v[22:23], off nt
	global_load_dword v91, v[24:25], off nt
	global_load_dword v92, v[26:27], off nt
	global_load_dword v93, v[28:29], off nt
	global_load_dword v94, v[48:49], off nt
	global_load_dword v95, v[50:51], off nt
	s_add_i32 s7, s7, 16
	v_add_u32_e32 v18, 0x400, v16
	s_waitcnt vmcnt(30)
; #define LAS __attribute__((address_space(3)))
; __device__ __forceinline__ unsigned pk2(float lo, float hi) { return pg8::cvt_pk_bf16(lo, hi); }
; __device__ __forceinline__ void transpose_item(const float* W, int K, int N, bf16_t* WT, int dst0, int src0, int mode, int nblk, LAS float* scr, int item, int lane) {
;     ...
;     for (int i = 0; i < 32; ++i) { const int kk = 2 * i + (lane >> 5); scr[kk * 33 + (lane & 31)] = __builtin_nontemporal_load(W + (size_t)(k0 + kk) * N + sc); }
;     asm volatile("s_waitcnt lgkmcnt(0)" ::: "memory");
;     const int c = lane & 7;
; #pragma unroll
;     for (int j = 0; j < 4; ++j) { const int n = (lane >> 3) + 8 * j; const LAS float* s = scr + (8 * c) * 33 + n;
;         u32x4 o; o.x = pk2(s[0 * 33], s[1 * 33]); o.y = pk2(s[2 * 33], s[3 * 33]); o.z = pk2(s[4 * 33], s[5 * 33]); o.w = pk2(s[6 * 33], s[7 * 33]);
;         *(u32x4*)(WT + (size_t)(dst0 + n0 + n) * K + k0 + 8 * c) = o; }
;     asm volatile("s_waitcnt lgkmcnt(0)" ::: "memory");
	ds_write2_b32 v16, v64, v65 offset1:66
	s_waitcnt vmcnt(28)
	ds_write2_b32 v16, v66, v67 offset0:132 offset1:198
	s_waitcnt vmcnt(26)
	ds_write2_b32 v18, v68, v69 offset0:8 offset1:74
	s_waitcnt vmcnt(24)
	ds_write2_b32 v18, v70, v71 offset0:140 offset1:206
	v_add_u32_e32 v16, 0x840, v16
	v_add_u32_e32 v18, 0x400, v16
	s_waitcnt vmcnt(22)
	ds_write2_b32 v16, v72, v73 offset1:66
	s_waitcnt vmcnt(20)
	ds_write2_b32 v16, v74, v75 offset0:132 offset1:198
	s_waitcnt vmcnt(18)
	ds_write2_b32 v18, v76, v77 offset0:8 offset1:74
	s_waitcnt vmcnt(16)
	ds_write2_b32 v18, v78, v79 offset0:140 offset1:206
	v_add_u32_e32 v16, 0x840, v16
	v_add_u32_e32 v18, 0x400, v16
	s_waitcnt vmcnt(14)
	ds_write2_b32 v16, v80, v81 offset1:66
	s_waitcnt vmcnt(12)
	ds_write2_b32 v16, v82, v83 offset0:132 offset1:198
	s_waitcnt vmcnt(10)
	ds_write2_b32 v18, v84, v85 offset0:8 offset1:74
	s_waitcnt vmcnt(8)
	ds_write2_b32 v18, v86, v87 offset0:140 offset1:206
	v_add_u32_e32 v16, 0x840, v16
	v_add_u32_e32 v18, 0x400, v16
	s_waitcnt vmcnt(6)
	ds_write2_b32 v16, v88, v89 offset1:66
	s_waitcnt vmcnt(4)
	ds_write2_b32 v16, v90, v91 offset0:132 offset1:198
	s_waitcnt vmcnt(2)
	ds_write2_b32 v18, v92, v93 offset0:8 offset1:74
	s_waitcnt vmcnt(0)
	ds_write2_b32 v18, v94, v95 offset0:140 offset1:206
	v_add_u32_e32 v16, 0x840, v16
	s_cmp_lg_u32 s7, 64
	s_waitcnt lgkmcnt(0)
	ds_read2_b32 v[18:19], v33 offset0:33 offset1:41
	ds_read2_b32 v[20:21], v33 offset1:8
	ds_read2_b32 v[22:23], v33 offset0:66 offset1:74
	ds_read2_b32 v[24:25], v33 offset0:99 offset1:107
	ds_read2_b32 v[26:27], v33 offset0:132 offset1:140
	ds_read2_b32 v[28:29], v33 offset0:165 offset1:173
	ds_read2_b32 v[48:49], v33 offset0:198 offset1:206
	ds_read2_b32 v[50:51], v33 offset0:231 offset1:239
	s_addk_i32 s6, 0x1900
	s_ashr_i32 s21, s20, 31
	v_or_b32_e32 v0, s6, v157
	v_lshl_add_u64 v[52:53], s[20:21], 1, v[2:3]
	v_lshlrev_b64 v[54:55], 12, v[0:1]
	s_waitcnt lgkmcnt(6)
	v_cvt_pk_bf16_f32 v14, v20, v18
	s_waitcnt lgkmcnt(4)
	v_cvt_pk_bf16_f32 v15, v22, v24
	s_waitcnt lgkmcnt(2)
	v_cvt_pk_bf16_f32 v16, v26, v28
	s_waitcnt lgkmcnt(0)
	v_cvt_pk_bf16_f32 v17, v48, v50
	v_lshl_add_u64 v[54:55], v[52:53], 0, v[54:55]
	global_store_dwordx4 v[54:55], v[14:17], off
	v_or_b32_e32 v0, s6, v34
	s_nop 0
	v_cvt_pk_bf16_f32 v14, v21, v19
	v_cvt_pk_bf16_f32 v15, v23, v25
	v_cvt_pk_bf16_f32 v16, v27, v29
	v_cvt_pk_bf16_f32 v17, v49, v51
	ds_read2_b32 v[20:21], v33 offset0:49 offset1:57
	ds_read2_b32 v[22:23], v33 offset0:16 offset1:24
	ds_read2_b32 v[24:25], v33 offset0:82 offset1:90
	ds_read2_b32 v[26:27], v33 offset0:115 offset1:123
	ds_read2_b32 v[28:29], v33 offset0:148 offset1:156
	ds_read2_b32 v[48:49], v33 offset0:181 offset1:189
	ds_read2_b32 v[50:51], v33 offset0:214 offset1:222
	ds_read2_b32 v[54:55], v33 offset0:247 offset1:255
	v_lshlrev_b64 v[18:19], 12, v[0:1]
	v_lshl_add_u64 v[18:19], v[52:53], 0, v[18:19]
	v_or_b32_e32 v0, s6, v35
	global_store_dwordx4 v[18:19], v[14:17], off
	v_lshlrev_b64 v[18:19], 12, v[0:1]
	v_lshl_add_u64 v[18:19], v[52:53], 0, v[18:19]
	s_waitcnt lgkmcnt(6)
	v_cvt_pk_bf16_f32 v14, v22, v20
	s_waitcnt lgkmcnt(4)
	v_cvt_pk_bf16_f32 v15, v24, v26
	s_waitcnt lgkmcnt(2)
	v_cvt_pk_bf16_f32 v16, v28, v48
	s_waitcnt lgkmcnt(0)
	v_cvt_pk_bf16_f32 v17, v50, v54
	v_or_b32_e32 v0, s6, v36
	global_store_dwordx4 v[18:19], v[14:17], off
	v_lshlrev_b64 v[18:19], 12, v[0:1]
	v_lshl_add_u64 v[18:19], v[52:53], 0, v[18:19]
	v_cvt_pk_bf16_f32 v14, v23, v21
	v_cvt_pk_bf16_f32 v15, v25, v27
	v_cvt_pk_bf16_f32 v16, v29, v49
	v_cvt_pk_bf16_f32 v17, v51, v55
	global_store_dwordx4 v[18:19], v[14:17], off
	s_waitcnt lgkmcnt(0)
	s_mov_b32 s6, s24
	s_andn2_b64 vcc, exec, s[18:19]
	s_cbranch_vccnz .LBB0_300

; __device__ __forceinline__ void transpose_item(const float* W, int K, int N, bf16_t* WT, int dst0, int src0, int mode, int nblk, LAS float* scr, int item, int lane) {
;     ...
;     const int sc = srccol(mode, n0 + (lane & 31), src0);
; #pragma unroll 8
;     for (int i = 0; i < 32; ++i) { const int kk = 2 * i + (lane >> 5); scr[kk * 33 + (lane & 31)] = __builtin_nontemporal_load(W + (size_t)(k0 + kk) * N + sc); }
.LBB0_313:
	v_add_u32_e32 v17, s21, v0
	v_mad_i64_i32 v[18:19], s[22:23], v17, s26, v[14:15]
	v_add_u32_e32 v20, 2, v17
	v_add_u32_e32 v22, 4, v17
	v_add_u32_e32 v24, 6, v17
	v_add_u32_e32 v26, 8, v17
	v_add_u32_e32 v28, 10, v17
	v_add_u32_e32 v47, 12, v17
	v_add_u32_e32 v17, 14, v17
	v_mad_i64_i32 v[20:21], s[22:23], v20, s26, v[14:15]
	v_mad_i64_i32 v[22:23], s[22:23], v22, s26, v[14:15]
	v_mad_i64_i32 v[24:25], s[22:23], v24, s26, v[14:15]
	v_mad_i64_i32 v[26:27], s[22:23], v26, s26, v[14:15]
	v_mad_i64_i32 v[28:29], s[22:23], v28, s26, v[14:15]
	v_mad_i64_i32 v[48:49], s[22:23], v47, s26, v[14:15]
	v_mad_i64_i32 v[50:51], s[22:23], v17, s26, v[14:15]
	global_load_dword v64, v[18:19], off nt
	global_load_dword v65, v[20:21], off nt
	global_load_dword v66, v[22:23], off nt
	global_load_dword v67, v[24:25], off nt
	global_load_dword v68, v[26:27], off nt
	global_load_dword v69, v[28:29], off nt
	global_load_dword v70, v[48:49], off nt
	global_load_dword v71, v[50:51], off nt
	s_add_i32 s21, s21, 16
	v_add_u32_e32 v17, s21, v0
	v_mad_i64_i32 v[18:19], s[22:23], v17, s26, v[14:15]
	v_add_u32_e32 v20, 2, v17
	v_add_u32_e32 v22, 4, v17
	v_add_u32_e32 v24, 6, v17
	v_add_u32_e32 v26, 8, v17
	v_add_u32_e32 v28, 10, v17
	v_add_u32_e32 v47, 12, v17
	v_add_u32_e32 v17, 14, v17
	v_mad_i64_i32 v[20:21], s[22:23], v20, s26, v[14:15]
	v_mad_i64_i32 v[22:23], s[22:23], v22, s26, v[14:15]
	v_mad_i64_i32 v[24:25], s[22:23], v24, s26, v[14:15]
	v_mad_i64_i32 v[26:27], s[22:23], v26, s26, v[14:15]
	v_mad_i64_i32 v[28:29], s[22:23], v28, s26, v[14:15]
	v_mad_i64_i32 v[48:49], s[22:23], v47, s26, v[14:15]
	v_mad_i64_i32 v[50:51], s[22:23], v17, s26, v[14:15]
	global_load_dword v72, v[18:19], off nt
	global_load_dword v73, v[20:21], off nt
	global_load_dword v74, v[22:23], off nt
	global_load_dword v75, v[24:25], off nt
	global_load_dword v76, v[26:27], off nt
	global_load_dword v77, v[28:29], off nt
	global_load_dword v78, v[48:49], off nt
	global_load_dword v79, v[50:51], off nt
	s_add_i32 s21, s21, 16
	v_add_u32_e32 v17, s21, v0
	v_mad_i64_i32 v[18:19], s[22:23], v17, s26, v[14:15]
	v_add_u32_e32 v20, 2, v17
	v_add_u32_e32 v22, 4, v17
	v_add_u32_e32 v24, 6, v17
	v_add_u32_e32 v26, 8, v17
	v_add_u32_e32 v28, 10, v17
	v_add_u32_e32 v47, 12, v17
	v_add_u32_e32 v17, 14, v17
	v_mad_i64_i32 v[20:21], s[22:23], v20, s26, v[14:15]
	v_mad_i64_i32 v[22:23], s[22:23], v22, s26, v[14:15]
	v_mad_i64_i32 v[24:25], s[22:23], v24, s26, v[14:15]
	v_mad_i64_i32 v[26:27], s[22:23], v26, s26, v[14:15]
	v_mad_i64_i32 v[28:29], s[22:23], v28, s26, v[14:15]
	v_mad_i64_i32 v[48:49], s[22:23], v47, s26, v[14:15]
	v_mad_i64_i32 v[50:51], s[22:23], v17, s26, v[14:15]
	global_load_dword v80, v[18:19], off nt
	global_load_dword v81, v[20:21], off nt
	global_load_dword v82, v[22:23], off nt
	global_load_dword v83, v[24:25], off nt
	global_load_dword v84, v[26:27], off nt
	global_load_dword v85, v[28:29], off nt
	global_load_dword v86, v[48:49], off nt
	global_load_dword v87, v[50:51], off nt
	s_add_i32 s21, s21, 16
	v_add_u32_e32 v17, s21, v0
	v_mad_i64_i32 v[18:19], s[22:23], v17, s26, v[14:15]
	v_add_u32_e32 v20, 2, v17
	v_add_u32_e32 v22, 4, v17
	v_add_u32_e32 v24, 6, v17
	v_add_u32_e32 v26, 8, v17
	v_add_u32_e32 v28, 10, v17
	v_add_u32_e32 v47, 12, v17
	v_add_u32_e32 v17, 14, v17
	v_mad_i64_i32 v[20:21], s[22:23], v20, s26, v[14:15]
	v_mad_i64_i32 v[22:23], s[22:23], v22, s26, v[14:15]
	v_mad_i64_i32 v[24:25], s[22:23], v24, s26, v[14:15]
	v_mad_i64_i32 v[26:27], s[22:23], v26, s26, v[14:15]
	v_mad_i64_i32 v[28:29], s[22:23], v28, s26, v[14:15]
	v_mad_i64_i32 v[48:49], s[22:23], v47, s26, v[14:15]
	v_mad_i64_i32 v[50:51], s[22:23], v17, s26, v[14:15]
	global_load_dword v88, v[18:19], off nt
	global_load_dword v89, v[20:21], off nt
	global_load_dword v90, v[22:23], off nt
	global_load_dword v91, v[24:25], off nt
	global_load_dword v92, v[26:27], off nt
	global_load_dword v93, v[28:29], off nt
	global_load_dword v94, v[48:49], off nt
	global_load_dword v95, v[50:51], off nt
	s_add_i32 s21, s21, 16
	v_add_u32_e32 v18, 0x400, v16
	s_waitcnt vmcnt(30)
; #define LAS __attribute__((address_space(3)))
; __device__ __forceinline__ unsigned pk2(float lo, float hi) { return pg8::cvt_pk_bf16(lo, hi); }
; __device__ __forceinline__ void transpose_item(const float* W, int K, int N, bf16_t* WT, int dst0, int src0, int mode, int nblk, LAS float* scr, int item, int lane) {
;     ...
;     for (int i = 0; i < 32; ++i) { const int kk = 2 * i + (lane >> 5); scr[kk * 33 + (lane & 31)] = __builtin_nontemporal_load(W + (size_t)(k0 + kk) * N + sc); }
;     asm volatile("s_waitcnt lgkmcnt(0)" ::: "memory");
;     const int c = lane & 7;
; #pragma unroll
;     for (int j = 0; j < 4; ++j) { const int n = (lane >> 3) + 8 * j; const LAS float* s = scr + (8 * c) * 33 + n;
;         u32x4 o; o.x = pk2(s[0 * 33], s[1 * 33]); o.y = pk2(s[2 * 33], s[3 * 33]); o.z = pk2(s[4 * 33], s[5 * 33]); o.w = pk2(s[6 * 33], s[7 * 33]);
;         *(u32x4*)(WT + (size_t)(dst0 + n0 + n) * K + k0 + 8 * c) = o; }
;     asm volatile("s_waitcnt lgkmcnt(0)" ::: "memory");
	ds_write2_b32 v16, v64, v65 offset1:66
	s_waitcnt vmcnt(28)
	ds_write2_b32 v16, v66, v67 offset0:132 offset1:198
	s_waitcnt vmcnt(26)
	ds_write2_b32 v18, v68, v69 offset0:8 offset1:74
	s_waitcnt vmcnt(24)
	ds_write2_b32 v18, v70, v71 offset0:140 offset1:206
	v_add_u32_e32 v16, 0x840, v16
	v_add_u32_e32 v18, 0x400, v16
	s_waitcnt vmcnt(22)
	ds_write2_b32 v16, v72, v73 offset1:66
	s_waitcnt vmcnt(20)
	ds_write2_b32 v16, v74, v75 offset0:132 offset1:198
	s_waitcnt vmcnt(18)
	ds_write2_b32 v18, v76, v77 offset0:8 offset1:74
	s_waitcnt vmcnt(16)
	ds_write2_b32 v18, v78, v79 offset0:140 offset1:206
	v_add_u32_e32 v16, 0x840, v16
	v_add_u32_e32 v18, 0x400, v16
	s_waitcnt vmcnt(14)
	ds_write2_b32 v16, v80, v81 offset1:66
	s_waitcnt vmcnt(12)
	ds_write2_b32 v16, v82, v83 offset0:132 offset1:198
	s_waitcnt vmcnt(10)
	ds_write2_b32 v18, v84, v85 offset0:8 offset1:74
	s_waitcnt vmcnt(8)
	ds_write2_b32 v18, v86, v87 offset0:140 offset1:206
	v_add_u32_e32 v16, 0x840, v16
	v_add_u32_e32 v18, 0x400, v16
	s_waitcnt vmcnt(6)
	ds_write2_b32 v16, v88, v89 offset1:66
	s_waitcnt vmcnt(4)
	ds_write2_b32 v16, v90, v91 offset0:132 offset1:198
	s_waitcnt vmcnt(2)
	ds_write2_b32 v18, v92, v93 offset0:8 offset1:74
	s_waitcnt vmcnt(0)
	ds_write2_b32 v18, v94, v95 offset0:140 offset1:206
	v_add_u32_e32 v16, 0x840, v16
	s_cmp_lg_u32 s21, 64
	s_waitcnt lgkmcnt(0)
	ds_read2_b32 v[18:19], v33 offset0:33 offset1:41
	ds_read2_b32 v[20:21], v33 offset1:8
	ds_read2_b32 v[22:23], v33 offset0:66 offset1:74
	ds_read2_b32 v[24:25], v33 offset0:99 offset1:107
	ds_read2_b32 v[26:27], v33 offset0:132 offset1:140
	ds_read2_b32 v[28:29], v33 offset0:165 offset1:173
	ds_read2_b32 v[48:49], v33 offset0:198 offset1:206
	ds_read2_b32 v[50:51], v33 offset0:231 offset1:239
	s_addk_i32 s7, 0x2500
	s_ashr_i32 s21, s20, 31
	v_or_b32_e32 v0, s7, v157
	v_lshl_add_u64 v[52:53], s[20:21], 1, v[2:3]
	v_lshlrev_b64 v[54:55], 12, v[0:1]
	s_waitcnt lgkmcnt(6)
	v_cvt_pk_bf16_f32 v14, v20, v18
	s_waitcnt lgkmcnt(4)
	v_cvt_pk_bf16_f32 v15, v22, v24
	s_waitcnt lgkmcnt(2)
	v_cvt_pk_bf16_f32 v16, v26, v28
	s_waitcnt lgkmcnt(0)
	v_cvt_pk_bf16_f32 v17, v48, v50
	v_lshl_add_u64 v[54:55], v[52:53], 0, v[54:55]
	global_store_dwordx4 v[54:55], v[14:17], off
	v_or_b32_e32 v0, s7, v34
	s_nop 0
	v_cvt_pk_bf16_f32 v14, v21, v19
	v_cvt_pk_bf16_f32 v15, v23, v25
	v_cvt_pk_bf16_f32 v16, v27, v29
	v_cvt_pk_bf16_f32 v17, v49, v51
	ds_read2_b32 v[20:21], v33 offset0:49 offset1:57
	ds_read2_b32 v[22:23], v33 offset0:16 offset1:24
	ds_read2_b32 v[24:25], v33 offset0:82 offset1:90
	ds_read2_b32 v[26:27], v33 offset0:115 offset1:123
	ds_read2_b32 v[28:29], v33 offset0:148 offset1:156
	ds_read2_b32 v[48:49], v33 offset0:181 offset1:189
	ds_read2_b32 v[50:51], v33 offset0:214 offset1:222
	ds_read2_b32 v[54:55], v33 offset0:247 offset1:255
	v_lshlrev_b64 v[18:19], 12, v[0:1]
	v_lshl_add_u64 v[18:19], v[52:53], 0, v[18:19]
	v_or_b32_e32 v0, s7, v35
	global_store_dwordx4 v[18:19], v[14:17], off
	v_lshlrev_b64 v[18:19], 12, v[0:1]
	v_lshl_add_u64 v[18:19], v[52:53], 0, v[18:19]
	s_waitcnt lgkmcnt(6)
	v_cvt_pk_bf16_f32 v14, v22, v20
	s_waitcnt lgkmcnt(4)
	v_cvt_pk_bf16_f32 v15, v24, v26
	s_waitcnt lgkmcnt(2)
	v_cvt_pk_bf16_f32 v16, v28, v48
	s_waitcnt lgkmcnt(0)
	v_cvt_pk_bf16_f32 v17, v50, v54
	v_or_b32_e32 v0, s7, v36
	global_store_dwordx4 v[18:19], v[14:17], off
	v_lshlrev_b64 v[18:19], 12, v[0:1]
	v_lshl_add_u64 v[18:19], v[52:53], 0, v[18:19]
	v_cvt_pk_bf16_f32 v14, v23, v21
	v_cvt_pk_bf16_f32 v15, v25, v27
	v_cvt_pk_bf16_f32 v16, v29, v49
	v_cvt_pk_bf16_f32 v17, v51, v55
	global_store_dwordx4 v[18:19], v[14:17], off
	s_waitcnt lgkmcnt(0)
	s_mov_b32 s7, s6
	s_andn2_b64 vcc, exec, s[18:19]
	s_cbranch_vccnz .LBB0_300

; #define LAS __attribute__((address_space(3)))
; __device__ __forceinline__ unsigned pk2(float lo, float hi) { return pg8::cvt_pk_bf16(lo, hi); }
; __device__ __forceinline__ void transpose_item(const float* W, int K, int N, bf16_t* WT, int dst0, int src0, int mode, int nblk, LAS float* scr, int item, int lane) {
;     ...
;     const int sc = srccol(mode, n0 + (lane & 31), src0);
; #pragma unroll 8
;     for (int i = 0; i < 32; ++i) { const int kk = 2 * i + (lane >> 5); scr[kk * 33 + (lane & 31)] = __builtin_nontemporal_load(W + (size_t)(k0 + kk) * N + sc); }
;     asm volatile("s_waitcnt lgkmcnt(0)" ::: "memory");
;     const int c = lane & 7;
; #pragma unroll
;     for (int j = 0; j < 4; ++j) { const int n = (lane >> 3) + 8 * j; const LAS float* s = scr + (8 * c) * 33 + n;
;         u32x4 o; o.x = pk2(s[0 * 33], s[1 * 33]); o.y = pk2(s[2 * 33], s[3 * 33]); o.z = pk2(s[4 * 33], s[5 * 33]); o.w = pk2(s[6 * 33], s[7 * 33]);
;         *(u32x4*)(WT + (size_t)(dst0 + n0 + n) * K + k0 + 8 * c) = o; }
;     asm volatile("s_waitcnt lgkmcnt(0)" ::: "memory");
.LBB0_320:
	v_lshl_add_u64 v[48:49], v[28:29], 0, s[22:23]
	v_lshl_add_u64 v[50:51], v[26:27], 0, s[22:23]
	v_lshl_add_u64 v[52:53], v[24:25], 0, s[22:23]
	v_lshl_add_u64 v[54:55], v[22:23], 0, s[22:23]
	v_lshl_add_u64 v[56:57], v[20:21], 0, s[22:23]
	v_lshl_add_u64 v[58:59], v[18:19], 0, s[22:23]
	v_lshl_add_u64 v[60:61], v[16:17], 0, s[22:23]
	v_lshl_add_u64 v[62:63], v[14:15], 0, s[22:23]
	global_load_dword v64, v[48:49], off nt
	global_load_dword v65, v[50:51], off nt
	global_load_dword v66, v[52:53], off nt
	global_load_dword v67, v[54:55], off nt
	global_load_dword v68, v[56:57], off nt
	global_load_dword v69, v[58:59], off nt
	global_load_dword v70, v[60:61], off nt
	global_load_dword v71, v[62:63], off nt
	s_add_u32 s22, s22, 0x130400
	s_addc_u32 s23, s23, 0
	v_lshl_add_u64 v[48:49], v[28:29], 0, s[22:23]
	v_lshl_add_u64 v[50:51], v[26:27], 0, s[22:23]
	v_lshl_add_u64 v[52:53], v[24:25], 0, s[22:23]
	v_lshl_add_u64 v[54:55], v[22:23], 0, s[22:23]
	v_lshl_add_u64 v[56:57], v[20:21], 0, s[22:23]
	v_lshl_add_u64 v[58:59], v[18:19], 0, s[22:23]
	v_lshl_add_u64 v[60:61], v[16:17], 0, s[22:23]
	v_lshl_add_u64 v[62:63], v[14:15], 0, s[22:23]
	global_load_dword v72, v[48:49], off nt
	global_load_dword v73, v[50:51], off nt
	global_load_dword v74, v[52:53], off nt
	global_load_dword v75, v[54:55], off nt
	global_load_dword v76, v[56:57], off nt
	global_load_dword v77, v[58:59], off nt
	global_load_dword v78, v[60:61], off nt
	global_load_dword v79, v[62:63], off nt
	s_add_u32 s22, s22, 0x130400
	s_addc_u32 s23, s23, 0
	v_lshl_add_u64 v[48:49], v[28:29], 0, s[22:23]
	v_lshl_add_u64 v[50:51], v[26:27], 0, s[22:23]
	v_lshl_add_u64 v[52:53], v[24:25], 0, s[22:23]
	v_lshl_add_u64 v[54:55], v[22:23], 0, s[22:23]
	v_lshl_add_u64 v[56:57], v[20:21], 0, s[22:23]
	v_lshl_add_u64 v[58:59], v[18:19], 0, s[22:23]
	v_lshl_add_u64 v[60:61], v[16:17], 0, s[22:23]
	v_lshl_add_u64 v[62:63], v[14:15], 0, s[22:23]
	global_load_dword v80, v[48:49], off nt
	global_load_dword v81, v[50:51], off nt
	global_load_dword v82, v[52:53], off nt
	global_load_dword v83, v[54:55], off nt
	global_load_dword v84, v[56:57], off nt
	global_load_dword v85, v[58:59], off nt
	global_load_dword v86, v[60:61], off nt
	global_load_dword v87, v[62:63], off nt
	s_add_u32 s22, s22, 0x130400
	s_addc_u32 s23, s23, 0
	v_lshl_add_u64 v[48:49], v[28:29], 0, s[22:23]
	v_lshl_add_u64 v[50:51], v[26:27], 0, s[22:23]
	v_lshl_add_u64 v[52:53], v[24:25], 0, s[22:23]
	v_lshl_add_u64 v[54:55], v[22:23], 0, s[22:23]
	v_lshl_add_u64 v[56:57], v[20:21], 0, s[22:23]
	v_lshl_add_u64 v[58:59], v[18:19], 0, s[22:23]
	v_lshl_add_u64 v[60:61], v[16:17], 0, s[22:23]
	v_lshl_add_u64 v[62:63], v[14:15], 0, s[22:23]
	global_load_dword v88, v[48:49], off nt
	global_load_dword v89, v[50:51], off nt
	global_load_dword v90, v[52:53], off nt
	global_load_dword v91, v[54:55], off nt
	global_load_dword v92, v[56:57], off nt
	global_load_dword v93, v[58:59], off nt
	global_load_dword v94, v[60:61], off nt
	global_load_dword v95, v[62:63], off nt
	s_add_u32 s22, s22, 0x130400
	s_addc_u32 s23, s23, 0
	v_add_u32_e32 v48, 0x400, v0
	s_waitcnt vmcnt(30)
	ds_write2_b32 v0, v64, v65 offset1:66
	s_waitcnt vmcnt(28)
	ds_write2_b32 v0, v66, v67 offset0:132 offset1:198
	s_waitcnt vmcnt(26)
	ds_write2_b32 v48, v68, v69 offset0:8 offset1:74
	s_waitcnt vmcnt(24)
	ds_write2_b32 v48, v70, v71 offset0:140 offset1:206
	v_add_u32_e32 v0, 0x840, v0
	v_add_u32_e32 v48, 0x400, v0
	s_waitcnt vmcnt(22)
	ds_write2_b32 v0, v72, v73 offset1:66
	s_waitcnt vmcnt(20)
	ds_write2_b32 v0, v74, v75 offset0:132 offset1:198
	s_waitcnt vmcnt(18)
	ds_write2_b32 v48, v76, v77 offset0:8 offset1:74
	s_waitcnt vmcnt(16)
	ds_write2_b32 v48, v78, v79 offset0:140 offset1:206
	v_add_u32_e32 v0, 0x840, v0
	v_add_u32_e32 v48, 0x400, v0
	s_waitcnt vmcnt(14)
	ds_write2_b32 v0, v80, v81 offset1:66
	s_waitcnt vmcnt(12)
	ds_write2_b32 v0, v82, v83 offset0:132 offset1:198
	s_waitcnt vmcnt(10)
	ds_write2_b32 v48, v84, v85 offset0:8 offset1:74
	s_waitcnt vmcnt(8)
	ds_write2_b32 v48, v86, v87 offset0:140 offset1:206
	v_add_u32_e32 v0, 0x840, v0
	v_add_u32_e32 v48, 0x400, v0
	s_waitcnt vmcnt(6)
	ds_write2_b32 v0, v88, v89 offset1:66
	s_waitcnt vmcnt(4)
	ds_write2_b32 v0, v90, v91 offset0:132 offset1:198
	s_waitcnt vmcnt(2)
	ds_write2_b32 v48, v92, v93 offset0:8 offset1:74
	s_waitcnt vmcnt(0)
	ds_write2_b32 v48, v94, v95 offset0:140 offset1:206
	v_add_u32_e32 v0, 0x840, v0
	s_cmp_lg_u32 s22, 0x4c1000
	s_waitcnt lgkmcnt(0)
	ds_read2_b32 v[18:19], v33 offset0:33 offset1:41
	ds_read2_b32 v[20:21], v33 offset1:8
	ds_read2_b32 v[22:23], v33 offset0:66 offset1:74
	ds_read2_b32 v[24:25], v33 offset0:99 offset1:107
	ds_read2_b32 v[26:27], v33 offset0:132 offset1:140
	ds_read2_b32 v[28:29], v33 offset0:165 offset1:173
	ds_read2_b32 v[48:49], v33 offset0:198 offset1:206
	ds_read2_b32 v[50:51], v33 offset0:231 offset1:239
	s_addk_i32 s6, 0x3100
	s_ashr_i32 s21, s20, 31
	v_or_b32_e32 v0, s6, v157
	v_lshl_add_u64 v[52:53], s[20:21], 1, v[2:3]
	v_lshlrev_b64 v[54:55], 12, v[0:1]
	s_waitcnt lgkmcnt(6)
	v_cvt_pk_bf16_f32 v14, v20, v18
	s_waitcnt lgkmcnt(4)
	v_cvt_pk_bf16_f32 v15, v22, v24
	s_waitcnt lgkmcnt(2)
	v_cvt_pk_bf16_f32 v16, v26, v28
	s_waitcnt lgkmcnt(0)
	v_cvt_pk_bf16_f32 v17, v48, v50
	v_lshl_add_u64 v[54:55], v[52:53], 0, v[54:55]
	global_store_dwordx4 v[54:55], v[14:17], off
	v_or_b32_e32 v0, s6, v34
	s_nop 0
	v_cvt_pk_bf16_f32 v14, v21, v19
	v_cvt_pk_bf16_f32 v15, v23, v25
	v_cvt_pk_bf16_f32 v16, v27, v29
	v_cvt_pk_bf16_f32 v17, v49, v51
	ds_read2_b32 v[20:21], v33 offset0:49 offset1:57
	ds_read2_b32 v[22:23], v33 offset0:16 offset1:24
	ds_read2_b32 v[24:25], v33 offset0:82 offset1:90
	ds_read2_b32 v[26:27], v33 offset0:115 offset1:123
	ds_read2_b32 v[28:29], v33 offset0:148 offset1:156
	ds_read2_b32 v[48:49], v33 offset0:181 offset1:189
	ds_read2_b32 v[50:51], v33 offset0:214 offset1:222
	ds_read2_b32 v[54:55], v33 offset0:247 offset1:255
	v_lshlrev_b64 v[18:19], 12, v[0:1]
	v_lshl_add_u64 v[18:19], v[52:53], 0, v[18:19]
	v_or_b32_e32 v0, s6, v35
	global_store_dwordx4 v[18:19], v[14:17], off
	v_lshlrev_b64 v[18:19], 12, v[0:1]
	v_lshl_add_u64 v[18:19], v[52:53], 0, v[18:19]
	s_waitcnt lgkmcnt(6)
	v_cvt_pk_bf16_f32 v14, v22, v20
	s_waitcnt lgkmcnt(4)
	v_cvt_pk_bf16_f32 v15, v24, v26
	s_waitcnt lgkmcnt(2)
	v_cvt_pk_bf16_f32 v16, v28, v48
	s_waitcnt lgkmcnt(0)
	v_cvt_pk_bf16_f32 v17, v50, v54
	v_or_b32_e32 v0, s6, v36
	global_store_dwordx4 v[18:19], v[14:17], off
	v_lshlrev_b64 v[18:19], 12, v[0:1]
	v_lshl_add_u64 v[18:19], v[52:53], 0, v[18:19]
	v_cvt_pk_bf16_f32 v14, v23, v21
	v_cvt_pk_bf16_f32 v15, v25, v27
	v_cvt_pk_bf16_f32 v16, v29, v49
	v_cvt_pk_bf16_f32 v17, v51, v55
	global_store_dwordx4 v[18:19], v[14:17], off
	s_waitcnt lgkmcnt(0)
	s_mov_b32 s6, s7
	s_andn2_b64 vcc, exec, s[18:19]
	s_cbranch_vccnz .LBB0_300

; __device__ __forceinline__ void transpose_item(const float* W, int K, int N, bf16_t* WT, int dst0, int src0, int mode, int nblk, LAS float* scr, int item, int lane) {
;     ...
;     const int sc = srccol(mode, n0 + (lane & 31), src0);
; #pragma unroll 8
;     for (int i = 0; i < 32; ++i) { const int kk = 2 * i + (lane >> 5); scr[kk * 33 + (lane & 31)] = __builtin_nontemporal_load(W + (size_t)(k0 + kk) * N + sc); }
.LBB0_327:
	v_add_u32_e32 v18, s21, v0
	v_ashrrev_i32_e32 v19, 31, v18
	v_add_u32_e32 v20, 2, v18
	v_add_u32_e32 v22, 4, v18
	v_add_u32_e32 v24, 6, v18
	v_add_u32_e32 v26, 8, v18
	v_add_u32_e32 v28, 10, v18
	v_add_u32_e32 v48, 12, v18
	v_add_u32_e32 v50, 14, v18
	v_lshlrev_b64 v[18:19], 13, v[18:19]
	v_ashrrev_i32_e32 v21, 31, v20
	v_ashrrev_i32_e32 v23, 31, v22
	v_ashrrev_i32_e32 v25, 31, v24
	v_ashrrev_i32_e32 v27, 31, v26
	v_ashrrev_i32_e32 v29, 31, v28
	v_ashrrev_i32_e32 v49, 31, v48
	v_ashrrev_i32_e32 v51, 31, v50
	v_lshl_add_u64 v[18:19], v[14:15], 0, v[18:19]
	v_lshlrev_b64 v[20:21], 13, v[20:21]
	v_lshlrev_b64 v[22:23], 13, v[22:23]
	v_lshlrev_b64 v[24:25], 13, v[24:25]
	v_lshlrev_b64 v[26:27], 13, v[26:27]
	v_lshlrev_b64 v[28:29], 13, v[28:29]
	v_lshlrev_b64 v[48:49], 13, v[48:49]
	v_lshlrev_b64 v[50:51], 13, v[50:51]
	v_lshl_add_u64 v[20:21], v[14:15], 0, v[20:21]
	v_lshl_add_u64 v[22:23], v[14:15], 0, v[22:23]
	v_lshl_add_u64 v[24:25], v[14:15], 0, v[24:25]
	v_lshl_add_u64 v[26:27], v[14:15], 0, v[26:27]
	v_lshl_add_u64 v[28:29], v[14:15], 0, v[28:29]
	v_lshl_add_u64 v[48:49], v[14:15], 0, v[48:49]
	v_lshl_add_u64 v[50:51], v[14:15], 0, v[50:51]
	global_load_dword v64, v[18:19], off nt
	global_load_dword v65, v[20:21], off nt
	global_load_dword v66, v[22:23], off nt
	global_load_dword v67, v[24:25], off nt
	global_load_dword v68, v[26:27], off nt
	global_load_dword v69, v[28:29], off nt
	global_load_dword v70, v[48:49], off nt
	global_load_dword v71, v[50:51], off nt
	s_add_i32 s21, s21, 16
	v_add_u32_e32 v18, s21, v0
	v_ashrrev_i32_e32 v19, 31, v18
	v_add_u32_e32 v20, 2, v18
	v_add_u32_e32 v22, 4, v18
	v_add_u32_e32 v24, 6, v18
	v_add_u32_e32 v26, 8, v18
	v_add_u32_e32 v28, 10, v18
	v_add_u32_e32 v48, 12, v18
	v_add_u32_e32 v50, 14, v18
	v_lshlrev_b64 v[18:19], 13, v[18:19]
	v_ashrrev_i32_e32 v21, 31, v20
	v_ashrrev_i32_e32 v23, 31, v22
	v_ashrrev_i32_e32 v25, 31, v24
	v_ashrrev_i32_e32 v27, 31, v26
	v_ashrrev_i32_e32 v29, 31, v28
	v_ashrrev_i32_e32 v49, 31, v48
	v_ashrrev_i32_e32 v51, 31, v50
	v_lshl_add_u64 v[18:19], v[14:15], 0, v[18:19]
	v_lshlrev_b64 v[20:21], 13, v[20:21]
	v_lshlrev_b64 v[22:23], 13, v[22:23]
	v_lshlrev_b64 v[24:25], 13, v[24:25]
	v_lshlrev_b64 v[26:27], 13, v[26:27]
	v_lshlrev_b64 v[28:29], 13, v[28:29]
	v_lshlrev_b64 v[48:49], 13, v[48:49]
	v_lshlrev_b64 v[50:51], 13, v[50:51]
	v_lshl_add_u64 v[20:21], v[14:15], 0, v[20:21]
	v_lshl_add_u64 v[22:23], v[14:15], 0, v[22:23]
	v_lshl_add_u64 v[24:25], v[14:15], 0, v[24:25]
	v_lshl_add_u64 v[26:27], v[14:15], 0, v[26:27]
	v_lshl_add_u64 v[28:29], v[14:15], 0, v[28:29]
	v_lshl_add_u64 v[48:49], v[14:15], 0, v[48:49]
	v_lshl_add_u64 v[50:51], v[14:15], 0, v[50:51]
	global_load_dword v72, v[18:19], off nt
	global_load_dword v73, v[20:21], off nt
	global_load_dword v74, v[22:23], off nt
	global_load_dword v75, v[24:25], off nt
	global_load_dword v76, v[26:27], off nt
	global_load_dword v77, v[28:29], off nt
	global_load_dword v78, v[48:49], off nt
	global_load_dword v79, v[50:51], off nt
	s_add_i32 s21, s21, 16
	v_add_u32_e32 v18, s21, v0
	v_ashrrev_i32_e32 v19, 31, v18
	v_add_u32_e32 v20, 2, v18
	v_add_u32_e32 v22, 4, v18
	v_add_u32_e32 v24, 6, v18
	v_add_u32_e32 v26, 8, v18
	v_add_u32_e32 v28, 10, v18
	v_add_u32_e32 v48, 12, v18
	v_add_u32_e32 v50, 14, v18
	v_lshlrev_b64 v[18:19], 13, v[18:19]
	v_ashrrev_i32_e32 v21, 31, v20
	v_ashrrev_i32_e32 v23, 31, v22
	v_ashrrev_i32_e32 v25, 31, v24
	v_ashrrev_i32_e32 v27, 31, v26
	v_ashrrev_i32_e32 v29, 31, v28
	v_ashrrev_i32_e32 v49, 31, v48
	v_ashrrev_i32_e32 v51, 31, v50
	v_lshl_add_u64 v[18:19], v[14:15], 0, v[18:19]
	v_lshlrev_b64 v[20:21], 13, v[20:21]
	v_lshlrev_b64 v[22:23], 13, v[22:23]
	v_lshlrev_b64 v[24:25], 13, v[24:25]
	v_lshlrev_b64 v[26:27], 13, v[26:27]
	v_lshlrev_b64 v[28:29], 13, v[28:29]
	v_lshlrev_b64 v[48:49], 13, v[48:49]
	v_lshlrev_b64 v[50:51], 13, v[50:51]
	v_lshl_add_u64 v[20:21], v[14:15], 0, v[20:21]
	v_lshl_add_u64 v[22:23], v[14:15], 0, v[22:23]
	v_lshl_add_u64 v[24:25], v[14:15], 0, v[24:25]
	v_lshl_add_u64 v[26:27], v[14:15], 0, v[26:27]
	v_lshl_add_u64 v[28:29], v[14:15], 0, v[28:29]
	v_lshl_add_u64 v[48:49], v[14:15], 0, v[48:49]
	v_lshl_add_u64 v[50:51], v[14:15], 0, v[50:51]
	global_load_dword v80, v[18:19], off nt
	global_load_dword v81, v[20:21], off nt
	global_load_dword v82, v[22:23], off nt
	global_load_dword v83, v[24:25], off nt
	global_load_dword v84, v[26:27], off nt
	global_load_dword v85, v[28:29], off nt
	global_load_dword v86, v[48:49], off nt
	global_load_dword v87, v[50:51], off nt
	s_add_i32 s21, s21, 16
	v_add_u32_e32 v18, s21, v0
	v_ashrrev_i32_e32 v19, 31, v18
	v_add_u32_e32 v20, 2, v18
	v_add_u32_e32 v22, 4, v18
	v_add_u32_e32 v24, 6, v18
	v_add_u32_e32 v26, 8, v18
	v_add_u32_e32 v28, 10, v18
	v_add_u32_e32 v48, 12, v18
	v_add_u32_e32 v50, 14, v18
	v_lshlrev_b64 v[18:19], 13, v[18:19]
	v_ashrrev_i32_e32 v21, 31, v20
	v_ashrrev_i32_e32 v23, 31, v22
	v_ashrrev_i32_e32 v25, 31, v24
	v_ashrrev_i32_e32 v27, 31, v26
	v_ashrrev_i32_e32 v29, 31, v28
	v_ashrrev_i32_e32 v49, 31, v48
	v_ashrrev_i32_e32 v51, 31, v50
	v_lshl_add_u64 v[18:19], v[14:15], 0, v[18:19]
	v_lshlrev_b64 v[20:21], 13, v[20:21]
	v_lshlrev_b64 v[22:23], 13, v[22:23]
	v_lshlrev_b64 v[24:25], 13, v[24:25]
	v_lshlrev_b64 v[26:27], 13, v[26:27]
	v_lshlrev_b64 v[28:29], 13, v[28:29]
	v_lshlrev_b64 v[48:49], 13, v[48:49]
	v_lshlrev_b64 v[50:51], 13, v[50:51]
	v_lshl_add_u64 v[20:21], v[14:15], 0, v[20:21]
	v_lshl_add_u64 v[22:23], v[14:15], 0, v[22:23]
	v_lshl_add_u64 v[24:25], v[14:15], 0, v[24:25]
	v_lshl_add_u64 v[26:27], v[14:15], 0, v[26:27]
	v_lshl_add_u64 v[28:29], v[14:15], 0, v[28:29]
	v_lshl_add_u64 v[48:49], v[14:15], 0, v[48:49]
	v_lshl_add_u64 v[50:51], v[14:15], 0, v[50:51]
	global_load_dword v88, v[18:19], off nt
	global_load_dword v89, v[20:21], off nt
	global_load_dword v90, v[22:23], off nt
	global_load_dword v91, v[24:25], off nt
	global_load_dword v92, v[26:27], off nt
	global_load_dword v93, v[28:29], off nt
	global_load_dword v94, v[48:49], off nt
	global_load_dword v95, v[50:51], off nt
	s_add_i32 s21, s21, 16
	v_add_u32_e32 v18, 0x400, v16
	s_waitcnt vmcnt(30)
; #define LAS __attribute__((address_space(3)))
; __device__ __forceinline__ unsigned pk2(float lo, float hi) { return pg8::cvt_pk_bf16(lo, hi); }
; __device__ __forceinline__ void transpose_item(const float* W, int K, int N, bf16_t* WT, int dst0, int src0, int mode, int nblk, LAS float* scr, int item, int lane) {
;     ...
;     for (int i = 0; i < 32; ++i) { const int kk = 2 * i + (lane >> 5); scr[kk * 33 + (lane & 31)] = __builtin_nontemporal_load(W + (size_t)(k0 + kk) * N + sc); }
;     asm volatile("s_waitcnt lgkmcnt(0)" ::: "memory");
;     const int c = lane & 7;
; #pragma unroll
;     for (int j = 0; j < 4; ++j) { const int n = (lane >> 3) + 8 * j; const LAS float* s = scr + (8 * c) * 33 + n;
;         u32x4 o; o.x = pk2(s[0 * 33], s[1 * 33]); o.y = pk2(s[2 * 33], s[3 * 33]); o.z = pk2(s[4 * 33], s[5 * 33]); o.w = pk2(s[6 * 33], s[7 * 33]);
;         *(u32x4*)(WT + (size_t)(dst0 + n0 + n) * K + k0 + 8 * c) = o; }
;     asm volatile("s_waitcnt lgkmcnt(0)" ::: "memory");
	ds_write2_b32 v16, v64, v65 offset1:66
	s_waitcnt vmcnt(28)
	ds_write2_b32 v16, v66, v67 offset0:132 offset1:198
	s_waitcnt vmcnt(26)
	ds_write2_b32 v18, v68, v69 offset0:8 offset1:74
	s_waitcnt vmcnt(24)
	ds_write2_b32 v18, v70, v71 offset0:140 offset1:206
	v_add_u32_e32 v16, 0x840, v16
	v_add_u32_e32 v18, 0x400, v16
	s_waitcnt vmcnt(22)
	ds_write2_b32 v16, v72, v73 offset1:66
	s_waitcnt vmcnt(20)
	ds_write2_b32 v16, v74, v75 offset0:132 offset1:198
	s_waitcnt vmcnt(18)
	ds_write2_b32 v18, v76, v77 offset0:8 offset1:74
	s_waitcnt vmcnt(16)
	ds_write2_b32 v18, v78, v79 offset0:140 offset1:206
	v_add_u32_e32 v16, 0x840, v16
	v_add_u32_e32 v18, 0x400, v16
	s_waitcnt vmcnt(14)
	ds_write2_b32 v16, v80, v81 offset1:66
	s_waitcnt vmcnt(12)
	ds_write2_b32 v16, v82, v83 offset0:132 offset1:198
	s_waitcnt vmcnt(10)
	ds_write2_b32 v18, v84, v85 offset0:8 offset1:74
	s_waitcnt vmcnt(8)
	ds_write2_b32 v18, v86, v87 offset0:140 offset1:206
	v_add_u32_e32 v16, 0x840, v16
	v_add_u32_e32 v18, 0x400, v16
	s_waitcnt vmcnt(6)
	ds_write2_b32 v16, v88, v89 offset1:66
	s_waitcnt vmcnt(4)
	ds_write2_b32 v16, v90, v91 offset0:132 offset1:198
	s_waitcnt vmcnt(2)
	ds_write2_b32 v18, v92, v93 offset0:8 offset1:74
	s_waitcnt vmcnt(0)
	ds_write2_b32 v18, v94, v95 offset0:140 offset1:206
	v_add_u32_e32 v16, 0x840, v16
	s_cmp_lg_u32 s21, 64
	s_waitcnt lgkmcnt(0)
	ds_read2_b32 v[18:19], v33 offset0:33 offset1:41
	ds_read2_b32 v[20:21], v33 offset1:8
	ds_read2_b32 v[22:23], v33 offset0:66 offset1:74
	ds_read2_b32 v[24:25], v33 offset0:99 offset1:107
	ds_read2_b32 v[26:27], v33 offset0:132 offset1:140
	ds_read2_b32 v[28:29], v33 offset0:165 offset1:173
	ds_read2_b32 v[48:49], v33 offset0:198 offset1:206
	ds_read2_b32 v[50:51], v33 offset0:231 offset1:239
	v_or_b32_e32 v54, s7, v157
	s_ashr_i32 s21, s20, 31
	v_ashrrev_i32_e32 v55, 31, v54
	v_lshl_add_u64 v[52:53], s[20:21], 1, v[4:5]
	v_lshlrev_b64 v[54:55], 12, v[54:55]
	s_waitcnt lgkmcnt(6)
	v_cvt_pk_bf16_f32 v14, v20, v18
	s_waitcnt lgkmcnt(4)
	v_cvt_pk_bf16_f32 v15, v22, v24
	s_waitcnt lgkmcnt(2)
	v_cvt_pk_bf16_f32 v16, v26, v28
	s_waitcnt lgkmcnt(0)
	v_cvt_pk_bf16_f32 v17, v48, v50
	v_lshl_add_u64 v[54:55], v[52:53], 0, v[54:55]
	v_or_b32_e32 v18, s7, v34
	global_store_dwordx4 v[54:55], v[14:17], off
	s_nop 1
	v_cvt_pk_bf16_f32 v14, v21, v19
	v_ashrrev_i32_e32 v19, 31, v18
	v_cvt_pk_bf16_f32 v15, v23, v25
	v_cvt_pk_bf16_f32 v16, v27, v29
	v_cvt_pk_bf16_f32 v17, v49, v51
	v_lshlrev_b64 v[18:19], 12, v[18:19]
	ds_read2_b32 v[20:21], v33 offset0:49 offset1:57
	ds_read2_b32 v[22:23], v33 offset0:16 offset1:24
	ds_read2_b32 v[24:25], v33 offset0:82 offset1:90
	ds_read2_b32 v[26:27], v33 offset0:115 offset1:123
	ds_read2_b32 v[28:29], v33 offset0:148 offset1:156
	ds_read2_b32 v[48:49], v33 offset0:181 offset1:189
	ds_read2_b32 v[50:51], v33 offset0:214 offset1:222
	ds_read2_b32 v[54:55], v33 offset0:247 offset1:255
	v_lshl_add_u64 v[18:19], v[52:53], 0, v[18:19]
	global_store_dwordx4 v[18:19], v[14:17], off
	v_or_b32_e32 v18, s7, v35
	v_ashrrev_i32_e32 v19, 31, v18
	v_lshlrev_b64 v[18:19], 12, v[18:19]
	s_waitcnt lgkmcnt(6)
	v_cvt_pk_bf16_f32 v14, v22, v20
	s_waitcnt lgkmcnt(4)
	v_cvt_pk_bf16_f32 v15, v24, v26
	s_waitcnt lgkmcnt(2)
	v_cvt_pk_bf16_f32 v16, v28, v48
	s_waitcnt lgkmcnt(0)
	v_cvt_pk_bf16_f32 v17, v50, v54
	v_lshl_add_u64 v[18:19], v[52:53], 0, v[18:19]
	global_store_dwordx4 v[18:19], v[14:17], off
	v_or_b32_e32 v18, s7, v36
	v_ashrrev_i32_e32 v19, 31, v18
	v_lshlrev_b64 v[18:19], 12, v[18:19]
	v_cvt_pk_bf16_f32 v14, v23, v21
	v_cvt_pk_bf16_f32 v15, v25, v27
	v_cvt_pk_bf16_f32 v16, v29, v49
	v_cvt_pk_bf16_f32 v17, v51, v55
	v_lshl_add_u64 v[18:19], v[52:53], 0, v[18:19]
	global_store_dwordx4 v[18:19], v[14:17], off
	s_waitcnt lgkmcnt(0)
	s_mov_b32 s7, s6
	s_andn2_b64 vcc, exec, s[18:19]
	s_cbranch_vccnz .LBB0_300

; __device__ __forceinline__ void transpose_item(const float* W, int K, int N, bf16_t* WT, int dst0, int src0, int mode, int nblk, LAS float* scr, int item, int lane) {
;     ...
;     const int sc = srccol(mode, n0 + (lane & 31), src0);
; #pragma unroll 8
;     for (int i = 0; i < 32; ++i) { const int kk = 2 * i + (lane >> 5); scr[kk * 33 + (lane & 31)] = __builtin_nontemporal_load(W + (size_t)(k0 + kk) * N + sc); }
.LBB0_334:
	v_add_u32_e32 v18, s21, v0
	v_ashrrev_i32_e32 v19, 31, v18
	v_add_u32_e32 v20, 2, v18
	v_add_u32_e32 v22, 4, v18
	v_add_u32_e32 v24, 6, v18
	v_add_u32_e32 v26, 8, v18
	v_add_u32_e32 v28, 10, v18
	v_add_u32_e32 v48, 12, v18
	v_add_u32_e32 v50, 14, v18
	v_lshlrev_b64 v[18:19], 13, v[18:19]
	v_ashrrev_i32_e32 v21, 31, v20
	v_ashrrev_i32_e32 v23, 31, v22
	v_ashrrev_i32_e32 v25, 31, v24
	v_ashrrev_i32_e32 v27, 31, v26
	v_ashrrev_i32_e32 v29, 31, v28
	v_ashrrev_i32_e32 v49, 31, v48
	v_ashrrev_i32_e32 v51, 31, v50
	v_lshl_add_u64 v[18:19], v[14:15], 0, v[18:19]
	v_lshlrev_b64 v[20:21], 13, v[20:21]
	v_lshlrev_b64 v[22:23], 13, v[22:23]
	v_lshlrev_b64 v[24:25], 13, v[24:25]
	v_lshlrev_b64 v[26:27], 13, v[26:27]
	v_lshlrev_b64 v[28:29], 13, v[28:29]
	v_lshlrev_b64 v[48:49], 13, v[48:49]
	v_lshlrev_b64 v[50:51], 13, v[50:51]
	v_lshl_add_u64 v[20:21], v[14:15], 0, v[20:21]
	v_lshl_add_u64 v[22:23], v[14:15], 0, v[22:23]
	v_lshl_add_u64 v[24:25], v[14:15], 0, v[24:25]
	v_lshl_add_u64 v[26:27], v[14:15], 0, v[26:27]
	v_lshl_add_u64 v[28:29], v[14:15], 0, v[28:29]
	v_lshl_add_u64 v[48:49], v[14:15], 0, v[48:49]
	v_lshl_add_u64 v[50:51], v[14:15], 0, v[50:51]
	global_load_dword v64, v[18:19], off nt
	global_load_dword v65, v[20:21], off nt
	global_load_dword v66, v[22:23], off nt
	global_load_dword v67, v[24:25], off nt
	global_load_dword v68, v[26:27], off nt
	global_load_dword v69, v[28:29], off nt
	global_load_dword v70, v[48:49], off nt
	global_load_dword v71, v[50:51], off nt
	s_add_i32 s21, s21, 16
	v_add_u32_e32 v18, s21, v0
	v_ashrrev_i32_e32 v19, 31, v18
	v_add_u32_e32 v20, 2, v18
	v_add_u32_e32 v22, 4, v18
	v_add_u32_e32 v24, 6, v18
	v_add_u32_e32 v26, 8, v18
	v_add_u32_e32 v28, 10, v18
	v_add_u32_e32 v48, 12, v18
	v_add_u32_e32 v50, 14, v18
	v_lshlrev_b64 v[18:19], 13, v[18:19]
	v_ashrrev_i32_e32 v21, 31, v20
	v_ashrrev_i32_e32 v23, 31, v22
	v_ashrrev_i32_e32 v25, 31, v24
	v_ashrrev_i32_e32 v27, 31, v26
	v_ashrrev_i32_e32 v29, 31, v28
	v_ashrrev_i32_e32 v49, 31, v48
	v_ashrrev_i32_e32 v51, 31, v50
	v_lshl_add_u64 v[18:19], v[14:15], 0, v[18:19]
	v_lshlrev_b64 v[20:21], 13, v[20:21]
	v_lshlrev_b64 v[22:23], 13, v[22:23]
	v_lshlrev_b64 v[24:25], 13, v[24:25]
	v_lshlrev_b64 v[26:27], 13, v[26:27]
	v_lshlrev_b64 v[28:29], 13, v[28:29]
	v_lshlrev_b64 v[48:49], 13, v[48:49]
	v_lshlrev_b64 v[50:51], 13, v[50:51]
	v_lshl_add_u64 v[20:21], v[14:15], 0, v[20:21]
	v_lshl_add_u64 v[22:23], v[14:15], 0, v[22:23]
	v_lshl_add_u64 v[24:25], v[14:15], 0, v[24:25]
	v_lshl_add_u64 v[26:27], v[14:15], 0, v[26:27]
	v_lshl_add_u64 v[28:29], v[14:15], 0, v[28:29]
	v_lshl_add_u64 v[48:49], v[14:15], 0, v[48:49]
	v_lshl_add_u64 v[50:51], v[14:15], 0, v[50:51]
	global_load_dword v72, v[18:19], off nt
	global_load_dword v73, v[20:21], off nt
	global_load_dword v74, v[22:23], off nt
	global_load_dword v75, v[24:25], off nt
	global_load_dword v76, v[26:27], off nt
	global_load_dword v77, v[28:29], off nt
	global_load_dword v78, v[48:49], off nt
	global_load_dword v79, v[50:51], off nt
	s_add_i32 s21, s21, 16
	v_add_u32_e32 v18, s21, v0
	v_ashrrev_i32_e32 v19, 31, v18
	v_add_u32_e32 v20, 2, v18
	v_add_u32_e32 v22, 4, v18
	v_add_u32_e32 v24, 6, v18
	v_add_u32_e32 v26, 8, v18
	v_add_u32_e32 v28, 10, v18
	v_add_u32_e32 v48, 12, v18
	v_add_u32_e32 v50, 14, v18
	v_lshlrev_b64 v[18:19], 13, v[18:19]
	v_ashrrev_i32_e32 v21, 31, v20
	v_ashrrev_i32_e32 v23, 31, v22
	v_ashrrev_i32_e32 v25, 31, v24
	v_ashrrev_i32_e32 v27, 31, v26
	v_ashrrev_i32_e32 v29, 31, v28
	v_ashrrev_i32_e32 v49, 31, v48
	v_ashrrev_i32_e32 v51, 31, v50
	v_lshl_add_u64 v[18:19], v[14:15], 0, v[18:19]
	v_lshlrev_b64 v[20:21], 13, v[20:21]
	v_lshlrev_b64 v[22:23], 13, v[22:23]
	v_lshlrev_b64 v[24:25], 13, v[24:25]
	v_lshlrev_b64 v[26:27], 13, v[26:27]
	v_lshlrev_b64 v[28:29], 13, v[28:29]
	v_lshlrev_b64 v[48:49], 13, v[48:49]
	v_lshlrev_b64 v[50:51], 13, v[50:51]
	v_lshl_add_u64 v[20:21], v[14:15], 0, v[20:21]
	v_lshl_add_u64 v[22:23], v[14:15], 0, v[22:23]
	v_lshl_add_u64 v[24:25], v[14:15], 0, v[24:25]
	v_lshl_add_u64 v[26:27], v[14:15], 0, v[26:27]
	v_lshl_add_u64 v[28:29], v[14:15], 0, v[28:29]
	v_lshl_add_u64 v[48:49], v[14:15], 0, v[48:49]
	v_lshl_add_u64 v[50:51], v[14:15], 0, v[50:51]
	global_load_dword v80, v[18:19], off nt
	global_load_dword v81, v[20:21], off nt
	global_load_dword v82, v[22:23], off nt
	global_load_dword v83, v[24:25], off nt
	global_load_dword v84, v[26:27], off nt
	global_load_dword v85, v[28:29], off nt
	global_load_dword v86, v[48:49], off nt
	global_load_dword v87, v[50:51], off nt
	s_add_i32 s21, s21, 16
	v_add_u32_e32 v18, s21, v0
	v_ashrrev_i32_e32 v19, 31, v18
	v_add_u32_e32 v20, 2, v18
	v_add_u32_e32 v22, 4, v18
	v_add_u32_e32 v24, 6, v18
	v_add_u32_e32 v26, 8, v18
	v_add_u32_e32 v28, 10, v18
	v_add_u32_e32 v48, 12, v18
	v_add_u32_e32 v50, 14, v18
	v_lshlrev_b64 v[18:19], 13, v[18:19]
	v_ashrrev_i32_e32 v21, 31, v20
	v_ashrrev_i32_e32 v23, 31, v22
	v_ashrrev_i32_e32 v25, 31, v24
	v_ashrrev_i32_e32 v27, 31, v26
	v_ashrrev_i32_e32 v29, 31, v28
	v_ashrrev_i32_e32 v49, 31, v48
	v_ashrrev_i32_e32 v51, 31, v50
	v_lshl_add_u64 v[18:19], v[14:15], 0, v[18:19]
	v_lshlrev_b64 v[20:21], 13, v[20:21]
	v_lshlrev_b64 v[22:23], 13, v[22:23]
	v_lshlrev_b64 v[24:25], 13, v[24:25]
	v_lshlrev_b64 v[26:27], 13, v[26:27]
	v_lshlrev_b64 v[28:29], 13, v[28:29]
	v_lshlrev_b64 v[48:49], 13, v[48:49]
	v_lshlrev_b64 v[50:51], 13, v[50:51]
	v_lshl_add_u64 v[20:21], v[14:15], 0, v[20:21]
	v_lshl_add_u64 v[22:23], v[14:15], 0, v[22:23]
	v_lshl_add_u64 v[24:25], v[14:15], 0, v[24:25]
	v_lshl_add_u64 v[26:27], v[14:15], 0, v[26:27]
	v_lshl_add_u64 v[28:29], v[14:15], 0, v[28:29]
	v_lshl_add_u64 v[48:49], v[14:15], 0, v[48:49]
	v_lshl_add_u64 v[50:51], v[14:15], 0, v[50:51]
	global_load_dword v88, v[18:19], off nt
	global_load_dword v89, v[20:21], off nt
	global_load_dword v90, v[22:23], off nt
	global_load_dword v91, v[24:25], off nt
	global_load_dword v92, v[26:27], off nt
	global_load_dword v93, v[28:29], off nt
	global_load_dword v94, v[48:49], off nt
	global_load_dword v95, v[50:51], off nt
	s_add_i32 s21, s21, 16
	v_add_u32_e32 v18, 0x400, v16
	s_waitcnt vmcnt(30)
; #define LAS __attribute__((address_space(3)))
; __device__ __forceinline__ unsigned pk2(float lo, float hi) { return pg8::cvt_pk_bf16(lo, hi); }
; __device__ __forceinline__ void transpose_item(const float* W, int K, int N, bf16_t* WT, int dst0, int src0, int mode, int nblk, LAS float* scr, int item, int lane) {
;     ...
;     for (int i = 0; i < 32; ++i) { const int kk = 2 * i + (lane >> 5); scr[kk * 33 + (lane & 31)] = __builtin_nontemporal_load(W + (size_t)(k0 + kk) * N + sc); }
;     asm volatile("s_waitcnt lgkmcnt(0)" ::: "memory");
;     const int c = lane & 7;
; #pragma unroll
;     for (int j = 0; j < 4; ++j) { const int n = (lane >> 3) + 8 * j; const LAS float* s = scr + (8 * c) * 33 + n;
;         u32x4 o; o.x = pk2(s[0 * 33], s[1 * 33]); o.y = pk2(s[2 * 33], s[3 * 33]); o.z = pk2(s[4 * 33], s[5 * 33]); o.w = pk2(s[6 * 33], s[7 * 33]);
;         *(u32x4*)(WT + (size_t)(dst0 + n0 + n) * K + k0 + 8 * c) = o; }
;     asm volatile("s_waitcnt lgkmcnt(0)" ::: "memory");
	ds_write2_b32 v16, v64, v65 offset1:66
	s_waitcnt vmcnt(28)
	ds_write2_b32 v16, v66, v67 offset0:132 offset1:198
	s_waitcnt vmcnt(26)
	ds_write2_b32 v18, v68, v69 offset0:8 offset1:74
	s_waitcnt vmcnt(24)
	ds_write2_b32 v18, v70, v71 offset0:140 offset1:206
	v_add_u32_e32 v16, 0x840, v16
	v_add_u32_e32 v18, 0x400, v16
	s_waitcnt vmcnt(22)
	ds_write2_b32 v16, v72, v73 offset1:66
	s_waitcnt vmcnt(20)
	ds_write2_b32 v16, v74, v75 offset0:132 offset1:198
	s_waitcnt vmcnt(18)
	ds_write2_b32 v18, v76, v77 offset0:8 offset1:74
	s_waitcnt vmcnt(16)
	ds_write2_b32 v18, v78, v79 offset0:140 offset1:206
	v_add_u32_e32 v16, 0x840, v16
	v_add_u32_e32 v18, 0x400, v16
	s_waitcnt vmcnt(14)
	ds_write2_b32 v16, v80, v81 offset1:66
	s_waitcnt vmcnt(12)
	ds_write2_b32 v16, v82, v83 offset0:132 offset1:198
	s_waitcnt vmcnt(10)
	ds_write2_b32 v18, v84, v85 offset0:8 offset1:74
	s_waitcnt vmcnt(8)
	ds_write2_b32 v18, v86, v87 offset0:140 offset1:206
	v_add_u32_e32 v16, 0x840, v16
	v_add_u32_e32 v18, 0x400, v16
	s_waitcnt vmcnt(6)
	ds_write2_b32 v16, v88, v89 offset1:66
	s_waitcnt vmcnt(4)
	ds_write2_b32 v16, v90, v91 offset0:132 offset1:198
	s_waitcnt vmcnt(2)
	ds_write2_b32 v18, v92, v93 offset0:8 offset1:74
	s_waitcnt vmcnt(0)
	ds_write2_b32 v18, v94, v95 offset0:140 offset1:206
	v_add_u32_e32 v16, 0x840, v16
	s_cmp_lg_u32 s21, 64
	s_waitcnt lgkmcnt(0)
	ds_read2_b32 v[18:19], v33 offset0:33 offset1:41
	ds_read2_b32 v[20:21], v33 offset1:8
	ds_read2_b32 v[22:23], v33 offset0:66 offset1:74
	ds_read2_b32 v[24:25], v33 offset0:99 offset1:107
	ds_read2_b32 v[26:27], v33 offset0:132 offset1:140
	ds_read2_b32 v[28:29], v33 offset0:165 offset1:173
	ds_read2_b32 v[48:49], v33 offset0:198 offset1:206
	ds_read2_b32 v[50:51], v33 offset0:231 offset1:239
	v_or_b32_e32 v54, s6, v157
	s_ashr_i32 s21, s20, 31
	v_ashrrev_i32_e32 v55, 31, v54
	v_lshl_add_u64 v[52:53], s[20:21], 1, v[6:7]
	v_lshlrev_b64 v[54:55], 11, v[54:55]
	s_waitcnt lgkmcnt(6)
	v_cvt_pk_bf16_f32 v14, v20, v18
	s_waitcnt lgkmcnt(4)
	v_cvt_pk_bf16_f32 v15, v22, v24
	s_waitcnt lgkmcnt(2)
	v_cvt_pk_bf16_f32 v16, v26, v28
	s_waitcnt lgkmcnt(0)
	v_cvt_pk_bf16_f32 v17, v48, v50
	v_lshl_add_u64 v[54:55], v[52:53], 0, v[54:55]
	v_or_b32_e32 v18, s6, v34
	global_store_dwordx4 v[54:55], v[14:17], off
	s_nop 1
	v_cvt_pk_bf16_f32 v14, v21, v19
	v_ashrrev_i32_e32 v19, 31, v18
	v_cvt_pk_bf16_f32 v15, v23, v25
	v_cvt_pk_bf16_f32 v16, v27, v29
	v_cvt_pk_bf16_f32 v17, v49, v51
	v_lshlrev_b64 v[18:19], 11, v[18:19]
	ds_read2_b32 v[20:21], v33 offset0:49 offset1:57
	ds_read2_b32 v[22:23], v33 offset0:16 offset1:24
	ds_read2_b32 v[24:25], v33 offset0:82 offset1:90
	ds_read2_b32 v[26:27], v33 offset0:115 offset1:123
	ds_read2_b32 v[28:29], v33 offset0:148 offset1:156
	ds_read2_b32 v[48:49], v33 offset0:181 offset1:189
	ds_read2_b32 v[50:51], v33 offset0:214 offset1:222
	ds_read2_b32 v[54:55], v33 offset0:247 offset1:255
	v_lshl_add_u64 v[18:19], v[52:53], 0, v[18:19]
	global_store_dwordx4 v[18:19], v[14:17], off
	v_or_b32_e32 v18, s6, v35
	v_ashrrev_i32_e32 v19, 31, v18
	v_lshlrev_b64 v[18:19], 11, v[18:19]
	s_waitcnt lgkmcnt(6)
	v_cvt_pk_bf16_f32 v14, v22, v20
	s_waitcnt lgkmcnt(4)
	v_cvt_pk_bf16_f32 v15, v24, v26
	s_waitcnt lgkmcnt(2)
	v_cvt_pk_bf16_f32 v16, v28, v48
	s_waitcnt lgkmcnt(0)
	v_cvt_pk_bf16_f32 v17, v50, v54
	v_lshl_add_u64 v[18:19], v[52:53], 0, v[18:19]
	global_store_dwordx4 v[18:19], v[14:17], off
	v_or_b32_e32 v18, s6, v36
	v_ashrrev_i32_e32 v19, 31, v18
	v_lshlrev_b64 v[18:19], 11, v[18:19]
	v_cvt_pk_bf16_f32 v14, v23, v21
	v_cvt_pk_bf16_f32 v15, v25, v27
	v_cvt_pk_bf16_f32 v16, v29, v49
	v_cvt_pk_bf16_f32 v17, v51, v55
	v_lshl_add_u64 v[18:19], v[52:53], 0, v[18:19]
	global_store_dwordx4 v[18:19], v[14:17], off
	s_waitcnt lgkmcnt(0)
	s_mov_b32 s6, s7
	s_andn2_b64 vcc, exec, s[18:19]
	s_cbranch_vccnz .LBB0_300

; __device__ __forceinline__ void transpose_item(const float* W, int K, int N, bf16_t* WT, int dst0, int src0, int mode, int nblk, LAS float* scr, int item, int lane) {
;     ...
;     const int sc = srccol(mode, n0 + (lane & 31), src0);
; #pragma unroll 8
;     for (int i = 0; i < 32; ++i) { const int kk = 2 * i + (lane >> 5); scr[kk * 33 + (lane & 31)] = __builtin_nontemporal_load(W + (size_t)(k0 + kk) * N + sc); }
.LBB0_341:
	v_add_u32_e32 v18, s21, v0
	v_ashrrev_i32_e32 v19, 31, v18
	v_add_u32_e32 v20, 2, v18
	v_add_u32_e32 v22, 4, v18
	v_add_u32_e32 v24, 6, v18
	v_add_u32_e32 v26, 8, v18
	v_add_u32_e32 v28, 10, v18
	v_add_u32_e32 v48, 12, v18
	v_add_u32_e32 v50, 14, v18
	v_lshlrev_b64 v[18:19], 13, v[18:19]
	v_ashrrev_i32_e32 v21, 31, v20
	v_ashrrev_i32_e32 v23, 31, v22
	v_ashrrev_i32_e32 v25, 31, v24
	v_ashrrev_i32_e32 v27, 31, v26
	v_ashrrev_i32_e32 v29, 31, v28
	v_ashrrev_i32_e32 v49, 31, v48
	v_ashrrev_i32_e32 v51, 31, v50
	v_lshl_add_u64 v[18:19], v[14:15], 0, v[18:19]
	v_lshlrev_b64 v[20:21], 13, v[20:21]
	v_lshlrev_b64 v[22:23], 13, v[22:23]
	v_lshlrev_b64 v[24:25], 13, v[24:25]
	v_lshlrev_b64 v[26:27], 13, v[26:27]
	v_lshlrev_b64 v[28:29], 13, v[28:29]
	v_lshlrev_b64 v[48:49], 13, v[48:49]
	v_lshlrev_b64 v[50:51], 13, v[50:51]
	v_lshl_add_u64 v[20:21], v[14:15], 0, v[20:21]
	v_lshl_add_u64 v[22:23], v[14:15], 0, v[22:23]
	v_lshl_add_u64 v[24:25], v[14:15], 0, v[24:25]
	v_lshl_add_u64 v[26:27], v[14:15], 0, v[26:27]
	v_lshl_add_u64 v[28:29], v[14:15], 0, v[28:29]
	v_lshl_add_u64 v[48:49], v[14:15], 0, v[48:49]
	v_lshl_add_u64 v[50:51], v[14:15], 0, v[50:51]
	global_load_dword v64, v[18:19], off nt
	global_load_dword v65, v[20:21], off nt
	global_load_dword v66, v[22:23], off nt
	global_load_dword v67, v[24:25], off nt
	global_load_dword v68, v[26:27], off nt
	global_load_dword v69, v[28:29], off nt
	global_load_dword v70, v[48:49], off nt
	global_load_dword v71, v[50:51], off nt
	s_add_i32 s21, s21, 16
	v_add_u32_e32 v18, s21, v0
	v_ashrrev_i32_e32 v19, 31, v18
	v_add_u32_e32 v20, 2, v18
	v_add_u32_e32 v22, 4, v18
	v_add_u32_e32 v24, 6, v18
	v_add_u32_e32 v26, 8, v18
	v_add_u32_e32 v28, 10, v18
	v_add_u32_e32 v48, 12, v18
	v_add_u32_e32 v50, 14, v18
	v_lshlrev_b64 v[18:19], 13, v[18:19]
	v_ashrrev_i32_e32 v21, 31, v20
	v_ashrrev_i32_e32 v23, 31, v22
	v_ashrrev_i32_e32 v25, 31, v24
	v_ashrrev_i32_e32 v27, 31, v26
	v_ashrrev_i32_e32 v29, 31, v28
	v_ashrrev_i32_e32 v49, 31, v48
	v_ashrrev_i32_e32 v51, 31, v50
	v_lshl_add_u64 v[18:19], v[14:15], 0, v[18:19]
	v_lshlrev_b64 v[20:21], 13, v[20:21]
	v_lshlrev_b64 v[22:23], 13, v[22:23]
	v_lshlrev_b64 v[24:25], 13, v[24:25]
	v_lshlrev_b64 v[26:27], 13, v[26:27]
	v_lshlrev_b64 v[28:29], 13, v[28:29]
	v_lshlrev_b64 v[48:49], 13, v[48:49]
	v_lshlrev_b64 v[50:51], 13, v[50:51]
	v_lshl_add_u64 v[20:21], v[14:15], 0, v[20:21]
	v_lshl_add_u64 v[22:23], v[14:15], 0, v[22:23]
	v_lshl_add_u64 v[24:25], v[14:15], 0, v[24:25]
	v_lshl_add_u64 v[26:27], v[14:15], 0, v[26:27]
	v_lshl_add_u64 v[28:29], v[14:15], 0, v[28:29]
	v_lshl_add_u64 v[48:49], v[14:15], 0, v[48:49]
	v_lshl_add_u64 v[50:51], v[14:15], 0, v[50:51]
	global_load_dword v72, v[18:19], off nt
	global_load_dword v73, v[20:21], off nt
	global_load_dword v74, v[22:23], off nt
	global_load_dword v75, v[24:25], off nt
	global_load_dword v76, v[26:27], off nt
	global_load_dword v77, v[28:29], off nt
	global_load_dword v78, v[48:49], off nt
	global_load_dword v79, v[50:51], off nt
	s_add_i32 s21, s21, 16
	v_add_u32_e32 v18, s21, v0
	v_ashrrev_i32_e32 v19, 31, v18
	v_add_u32_e32 v20, 2, v18
	v_add_u32_e32 v22, 4, v18
	v_add_u32_e32 v24, 6, v18
	v_add_u32_e32 v26, 8, v18
	v_add_u32_e32 v28, 10, v18
	v_add_u32_e32 v48, 12, v18
	v_add_u32_e32 v50, 14, v18
	v_lshlrev_b64 v[18:19], 13, v[18:19]
	v_ashrrev_i32_e32 v21, 31, v20
	v_ashrrev_i32_e32 v23, 31, v22
	v_ashrrev_i32_e32 v25, 31, v24
	v_ashrrev_i32_e32 v27, 31, v26
	v_ashrrev_i32_e32 v29, 31, v28
	v_ashrrev_i32_e32 v49, 31, v48
	v_ashrrev_i32_e32 v51, 31, v50
	v_lshl_add_u64 v[18:19], v[14:15], 0, v[18:19]
	v_lshlrev_b64 v[20:21], 13, v[20:21]
	v_lshlrev_b64 v[22:23], 13, v[22:23]
	v_lshlrev_b64 v[24:25], 13, v[24:25]
	v_lshlrev_b64 v[26:27], 13, v[26:27]
	v_lshlrev_b64 v[28:29], 13, v[28:29]
	v_lshlrev_b64 v[48:49], 13, v[48:49]
	v_lshlrev_b64 v[50:51], 13, v[50:51]
	v_lshl_add_u64 v[20:21], v[14:15], 0, v[20:21]
	v_lshl_add_u64 v[22:23], v[14:15], 0, v[22:23]
	v_lshl_add_u64 v[24:25], v[14:15], 0, v[24:25]
	v_lshl_add_u64 v[26:27], v[14:15], 0, v[26:27]
	v_lshl_add_u64 v[28:29], v[14:15], 0, v[28:29]
	v_lshl_add_u64 v[48:49], v[14:15], 0, v[48:49]
	v_lshl_add_u64 v[50:51], v[14:15], 0, v[50:51]
	global_load_dword v80, v[18:19], off nt
	global_load_dword v81, v[20:21], off nt
	global_load_dword v82, v[22:23], off nt
	global_load_dword v83, v[24:25], off nt
	global_load_dword v84, v[26:27], off nt
	global_load_dword v85, v[28:29], off nt
	global_load_dword v86, v[48:49], off nt
	global_load_dword v87, v[50:51], off nt
	s_add_i32 s21, s21, 16
	v_add_u32_e32 v18, s21, v0
	v_ashrrev_i32_e32 v19, 31, v18
	v_add_u32_e32 v20, 2, v18
	v_add_u32_e32 v22, 4, v18
	v_add_u32_e32 v24, 6, v18
	v_add_u32_e32 v26, 8, v18
	v_add_u32_e32 v28, 10, v18
	v_add_u32_e32 v48, 12, v18
	v_add_u32_e32 v50, 14, v18
	v_lshlrev_b64 v[18:19], 13, v[18:19]
	v_ashrrev_i32_e32 v21, 31, v20
	v_ashrrev_i32_e32 v23, 31, v22
	v_ashrrev_i32_e32 v25, 31, v24
	v_ashrrev_i32_e32 v27, 31, v26
	v_ashrrev_i32_e32 v29, 31, v28
	v_ashrrev_i32_e32 v49, 31, v48
	v_ashrrev_i32_e32 v51, 31, v50
	v_lshl_add_u64 v[18:19], v[14:15], 0, v[18:19]
	v_lshlrev_b64 v[20:21], 13, v[20:21]
	v_lshlrev_b64 v[22:23], 13, v[22:23]
	v_lshlrev_b64 v[24:25], 13, v[24:25]
	v_lshlrev_b64 v[26:27], 13, v[26:27]
	v_lshlrev_b64 v[28:29], 13, v[28:29]
	v_lshlrev_b64 v[48:49], 13, v[48:49]
	v_lshlrev_b64 v[50:51], 13, v[50:51]
	v_lshl_add_u64 v[20:21], v[14:15], 0, v[20:21]
	v_lshl_add_u64 v[22:23], v[14:15], 0, v[22:23]
	v_lshl_add_u64 v[24:25], v[14:15], 0, v[24:25]
	v_lshl_add_u64 v[26:27], v[14:15], 0, v[26:27]
	v_lshl_add_u64 v[28:29], v[14:15], 0, v[28:29]
	v_lshl_add_u64 v[48:49], v[14:15], 0, v[48:49]
	v_lshl_add_u64 v[50:51], v[14:15], 0, v[50:51]
	global_load_dword v88, v[18:19], off nt
	global_load_dword v89, v[20:21], off nt
	global_load_dword v90, v[22:23], off nt
	global_load_dword v91, v[24:25], off nt
	global_load_dword v92, v[26:27], off nt
	global_load_dword v93, v[28:29], off nt
	global_load_dword v94, v[48:49], off nt
	global_load_dword v95, v[50:51], off nt
	s_add_i32 s21, s21, 16
	v_add_u32_e32 v18, 0x400, v16
	s_waitcnt vmcnt(30)
; #define LAS __attribute__((address_space(3)))
; __device__ __forceinline__ unsigned pk2(float lo, float hi) { return pg8::cvt_pk_bf16(lo, hi); }
; __device__ __forceinline__ void transpose_item(const float* W, int K, int N, bf16_t* WT, int dst0, int src0, int mode, int nblk, LAS float* scr, int item, int lane) {
;     ...
;     for (int i = 0; i < 32; ++i) { const int kk = 2 * i + (lane >> 5); scr[kk * 33 + (lane & 31)] = __builtin_nontemporal_load(W + (size_t)(k0 + kk) * N + sc); }
;     asm volatile("s_waitcnt lgkmcnt(0)" ::: "memory");
;     const int c = lane & 7;
; #pragma unroll
;     for (int j = 0; j < 4; ++j) { const int n = (lane >> 3) + 8 * j; const LAS float* s = scr + (8 * c) * 33 + n;
;         u32x4 o; o.x = pk2(s[0 * 33], s[1 * 33]); o.y = pk2(s[2 * 33], s[3 * 33]); o.z = pk2(s[4 * 33], s[5 * 33]); o.w = pk2(s[6 * 33], s[7 * 33]);
;         *(u32x4*)(WT + (size_t)(dst0 + n0 + n) * K + k0 + 8 * c) = o; }
;     asm volatile("s_waitcnt lgkmcnt(0)" ::: "memory");
	ds_write2_b32 v16, v64, v65 offset1:66
	s_waitcnt vmcnt(28)
	ds_write2_b32 v16, v66, v67 offset0:132 offset1:198
	s_waitcnt vmcnt(26)
	ds_write2_b32 v18, v68, v69 offset0:8 offset1:74
	s_waitcnt vmcnt(24)
	ds_write2_b32 v18, v70, v71 offset0:140 offset1:206
	v_add_u32_e32 v16, 0x840, v16
	v_add_u32_e32 v18, 0x400, v16
	s_waitcnt vmcnt(22)
	ds_write2_b32 v16, v72, v73 offset1:66
	s_waitcnt vmcnt(20)
	ds_write2_b32 v16, v74, v75 offset0:132 offset1:198
	s_waitcnt vmcnt(18)
	ds_write2_b32 v18, v76, v77 offset0:8 offset1:74
	s_waitcnt vmcnt(16)
	ds_write2_b32 v18, v78, v79 offset0:140 offset1:206
	v_add_u32_e32 v16, 0x840, v16
	v_add_u32_e32 v18, 0x400, v16
	s_waitcnt vmcnt(14)
	ds_write2_b32 v16, v80, v81 offset1:66
	s_waitcnt vmcnt(12)
	ds_write2_b32 v16, v82, v83 offset0:132 offset1:198
	s_waitcnt vmcnt(10)
	ds_write2_b32 v18, v84, v85 offset0:8 offset1:74
	s_waitcnt vmcnt(8)
	ds_write2_b32 v18, v86, v87 offset0:140 offset1:206
	v_add_u32_e32 v16, 0x840, v16
	v_add_u32_e32 v18, 0x400, v16
	s_waitcnt vmcnt(6)
	ds_write2_b32 v16, v88, v89 offset1:66
	s_waitcnt vmcnt(4)
	ds_write2_b32 v16, v90, v91 offset0:132 offset1:198
	s_waitcnt vmcnt(2)
	ds_write2_b32 v18, v92, v93 offset0:8 offset1:74
	s_waitcnt vmcnt(0)
	ds_write2_b32 v18, v94, v95 offset0:140 offset1:206
	v_add_u32_e32 v16, 0x840, v16
	s_cmp_lg_u32 s21, 64
	s_waitcnt lgkmcnt(0)
	ds_read2_b32 v[18:19], v33 offset0:33 offset1:41
	ds_read2_b32 v[20:21], v33 offset1:8
	ds_read2_b32 v[22:23], v33 offset0:66 offset1:74
	ds_read2_b32 v[24:25], v33 offset0:99 offset1:107
	ds_read2_b32 v[26:27], v33 offset0:132 offset1:140
	ds_read2_b32 v[28:29], v33 offset0:165 offset1:173
	ds_read2_b32 v[48:49], v33 offset0:198 offset1:206
	ds_read2_b32 v[50:51], v33 offset0:231 offset1:239
	v_or_b32_e32 v54, s7, v157
	s_ashr_i32 s21, s20, 31
	v_ashrrev_i32_e32 v55, 31, v54
	v_lshl_add_u64 v[52:53], s[20:21], 1, v[8:9]
	v_lshlrev_b64 v[54:55], 12, v[54:55]
	s_waitcnt lgkmcnt(6)
	v_cvt_pk_bf16_f32 v14, v20, v18
	s_waitcnt lgkmcnt(4)
	v_cvt_pk_bf16_f32 v15, v22, v24
	s_waitcnt lgkmcnt(2)
	v_cvt_pk_bf16_f32 v16, v26, v28
	s_waitcnt lgkmcnt(0)
	v_cvt_pk_bf16_f32 v17, v48, v50
	v_lshl_add_u64 v[54:55], v[52:53], 0, v[54:55]
	v_or_b32_e32 v18, s7, v34
	global_store_dwordx4 v[54:55], v[14:17], off
	s_nop 1
	v_cvt_pk_bf16_f32 v14, v21, v19
	v_ashrrev_i32_e32 v19, 31, v18
	v_cvt_pk_bf16_f32 v15, v23, v25
	v_cvt_pk_bf16_f32 v16, v27, v29
	v_cvt_pk_bf16_f32 v17, v49, v51
	v_lshlrev_b64 v[18:19], 12, v[18:19]
	ds_read2_b32 v[20:21], v33 offset0:49 offset1:57
	ds_read2_b32 v[22:23], v33 offset0:16 offset1:24
	ds_read2_b32 v[24:25], v33 offset0:82 offset1:90
	ds_read2_b32 v[26:27], v33 offset0:115 offset1:123
	ds_read2_b32 v[28:29], v33 offset0:148 offset1:156
	ds_read2_b32 v[48:49], v33 offset0:181 offset1:189
	ds_read2_b32 v[50:51], v33 offset0:214 offset1:222
	ds_read2_b32 v[54:55], v33 offset0:247 offset1:255
	v_lshl_add_u64 v[18:19], v[52:53], 0, v[18:19]
	global_store_dwordx4 v[18:19], v[14:17], off
	v_or_b32_e32 v18, s7, v35
	v_ashrrev_i32_e32 v19, 31, v18
	v_lshlrev_b64 v[18:19], 12, v[18:19]
	s_waitcnt lgkmcnt(6)
	v_cvt_pk_bf16_f32 v14, v22, v20
	s_waitcnt lgkmcnt(4)
	v_cvt_pk_bf16_f32 v15, v24, v26
	s_waitcnt lgkmcnt(2)
	v_cvt_pk_bf16_f32 v16, v28, v48
	s_waitcnt lgkmcnt(0)
	v_cvt_pk_bf16_f32 v17, v50, v54
	v_lshl_add_u64 v[18:19], v[52:53], 0, v[18:19]
	global_store_dwordx4 v[18:19], v[14:17], off
	v_or_b32_e32 v18, s7, v36
	v_ashrrev_i32_e32 v19, 31, v18
	v_lshlrev_b64 v[18:19], 12, v[18:19]
	v_cvt_pk_bf16_f32 v14, v23, v21
	v_cvt_pk_bf16_f32 v15, v25, v27
	v_cvt_pk_bf16_f32 v16, v29, v49
	v_cvt_pk_bf16_f32 v17, v51, v55
	v_lshl_add_u64 v[18:19], v[52:53], 0, v[18:19]
	global_store_dwordx4 v[18:19], v[14:17], off
	s_waitcnt lgkmcnt(0)
	s_mov_b32 s7, s6
	s_andn2_b64 vcc, exec, s[18:19]
	s_cbranch_vccnz .LBB0_300

; #define LAS __attribute__((address_space(3)))
; __device__ __forceinline__ unsigned pk2(float lo, float hi) { return pg8::cvt_pk_bf16(lo, hi); }
; __device__ __forceinline__ void transpose_item(const float* W, int K, int N, bf16_t* WT, int dst0, int src0, int mode, int nblk, LAS float* scr, int item, int lane) {
;     ...
;     const int sc = srccol(mode, n0 + (lane & 31), src0);
; #pragma unroll 8
;     for (int i = 0; i < 32; ++i) { const int kk = 2 * i + (lane >> 5); scr[kk * 33 + (lane & 31)] = __builtin_nontemporal_load(W + (size_t)(k0 + kk) * N + sc); }
;     asm volatile("s_waitcnt lgkmcnt(0)" ::: "memory");
;     const int c = lane & 7;
; #pragma unroll
;     for (int j = 0; j < 4; ++j) { const int n = (lane >> 3) + 8 * j; const LAS float* s = scr + (8 * c) * 33 + n;
;         u32x4 o; o.x = pk2(s[0 * 33], s[1 * 33]); o.y = pk2(s[2 * 33], s[3 * 33]); o.z = pk2(s[4 * 33], s[5 * 33]); o.w = pk2(s[6 * 33], s[7 * 33]);
;         *(u32x4*)(WT + (size_t)(dst0 + n0 + n) * K + k0 + 8 * c) = o; }
;     asm volatile("s_waitcnt lgkmcnt(0)" ::: "memory");
.LBB0_345:
	v_lshl_add_u64 v[48:49], v[28:29], 0, s[22:23]
	v_lshl_add_u64 v[50:51], v[26:27], 0, s[22:23]
	v_lshl_add_u64 v[52:53], v[24:25], 0, s[22:23]
	v_lshl_add_u64 v[54:55], v[22:23], 0, s[22:23]
	v_lshl_add_u64 v[56:57], v[20:21], 0, s[22:23]
	v_lshl_add_u64 v[58:59], v[18:19], 0, s[22:23]
	v_lshl_add_u64 v[60:61], v[16:17], 0, s[22:23]
	v_lshl_add_u64 v[62:63], v[14:15], 0, s[22:23]
	global_load_dword v64, v[48:49], off nt
	global_load_dword v65, v[50:51], off nt
	global_load_dword v66, v[52:53], off nt
	global_load_dword v67, v[54:55], off nt
	global_load_dword v68, v[56:57], off nt
	global_load_dword v69, v[58:59], off nt
	global_load_dword v70, v[60:61], off nt
	global_load_dword v71, v[62:63], off nt
	s_add_u32 s22, s22, 0xb0000
	s_addc_u32 s23, s23, 0
	v_lshl_add_u64 v[48:49], v[28:29], 0, s[22:23]
	v_lshl_add_u64 v[50:51], v[26:27], 0, s[22:23]
	v_lshl_add_u64 v[52:53], v[24:25], 0, s[22:23]
	v_lshl_add_u64 v[54:55], v[22:23], 0, s[22:23]
	v_lshl_add_u64 v[56:57], v[20:21], 0, s[22:23]
	v_lshl_add_u64 v[58:59], v[18:19], 0, s[22:23]
	v_lshl_add_u64 v[60:61], v[16:17], 0, s[22:23]
	v_lshl_add_u64 v[62:63], v[14:15], 0, s[22:23]
	global_load_dword v72, v[48:49], off nt
	global_load_dword v73, v[50:51], off nt
	global_load_dword v74, v[52:53], off nt
	global_load_dword v75, v[54:55], off nt
	global_load_dword v76, v[56:57], off nt
	global_load_dword v77, v[58:59], off nt
	global_load_dword v78, v[60:61], off nt
	global_load_dword v79, v[62:63], off nt
	s_add_u32 s22, s22, 0xb0000
	s_addc_u32 s23, s23, 0
	v_lshl_add_u64 v[48:49], v[28:29], 0, s[22:23]
	v_lshl_add_u64 v[50:51], v[26:27], 0, s[22:23]
	v_lshl_add_u64 v[52:53], v[24:25], 0, s[22:23]
	v_lshl_add_u64 v[54:55], v[22:23], 0, s[22:23]
	v_lshl_add_u64 v[56:57], v[20:21], 0, s[22:23]
	v_lshl_add_u64 v[58:59], v[18:19], 0, s[22:23]
	v_lshl_add_u64 v[60:61], v[16:17], 0, s[22:23]
	v_lshl_add_u64 v[62:63], v[14:15], 0, s[22:23]
	global_load_dword v80, v[48:49], off nt
	global_load_dword v81, v[50:51], off nt
	global_load_dword v82, v[52:53], off nt
	global_load_dword v83, v[54:55], off nt
	global_load_dword v84, v[56:57], off nt
	global_load_dword v85, v[58:59], off nt
	global_load_dword v86, v[60:61], off nt
	global_load_dword v87, v[62:63], off nt
	s_add_u32 s22, s22, 0xb0000
	s_addc_u32 s23, s23, 0
	v_lshl_add_u64 v[48:49], v[28:29], 0, s[22:23]
	v_lshl_add_u64 v[50:51], v[26:27], 0, s[22:23]
	v_lshl_add_u64 v[52:53], v[24:25], 0, s[22:23]
	v_lshl_add_u64 v[54:55], v[22:23], 0, s[22:23]
	v_lshl_add_u64 v[56:57], v[20:21], 0, s[22:23]
	v_lshl_add_u64 v[58:59], v[18:19], 0, s[22:23]
	v_lshl_add_u64 v[60:61], v[16:17], 0, s[22:23]
	v_lshl_add_u64 v[62:63], v[14:15], 0, s[22:23]
	global_load_dword v88, v[48:49], off nt
	global_load_dword v89, v[50:51], off nt
	global_load_dword v90, v[52:53], off nt
	global_load_dword v91, v[54:55], off nt
	global_load_dword v92, v[56:57], off nt
	global_load_dword v93, v[58:59], off nt
	global_load_dword v94, v[60:61], off nt
	global_load_dword v95, v[62:63], off nt
	s_add_u32 s22, s22, 0xb0000
	s_addc_u32 s23, s23, 0
	v_add_u32_e32 v48, 0x400, v0
	s_waitcnt vmcnt(30)
	ds_write2_b32 v0, v64, v65 offset1:66
	s_waitcnt vmcnt(28)
	ds_write2_b32 v0, v66, v67 offset0:132 offset1:198
	s_waitcnt vmcnt(26)
	ds_write2_b32 v48, v68, v69 offset0:8 offset1:74
	s_waitcnt vmcnt(24)
	ds_write2_b32 v48, v70, v71 offset0:140 offset1:206
	v_add_u32_e32 v0, 0x840, v0
	v_add_u32_e32 v48, 0x400, v0
	s_waitcnt vmcnt(22)
	ds_write2_b32 v0, v72, v73 offset1:66
	s_waitcnt vmcnt(20)
	ds_write2_b32 v0, v74, v75 offset0:132 offset1:198
	s_waitcnt vmcnt(18)
	ds_write2_b32 v48, v76, v77 offset0:8 offset1:74
	s_waitcnt vmcnt(16)
	ds_write2_b32 v48, v78, v79 offset0:140 offset1:206
	v_add_u32_e32 v0, 0x840, v0
	v_add_u32_e32 v48, 0x400, v0
	s_waitcnt vmcnt(14)
	ds_write2_b32 v0, v80, v81 offset1:66
	s_waitcnt vmcnt(12)
	ds_write2_b32 v0, v82, v83 offset0:132 offset1:198
	s_waitcnt vmcnt(10)
	ds_write2_b32 v48, v84, v85 offset0:8 offset1:74
	s_waitcnt vmcnt(8)
	ds_write2_b32 v48, v86, v87 offset0:140 offset1:206
	v_add_u32_e32 v0, 0x840, v0
	v_add_u32_e32 v48, 0x400, v0
	s_waitcnt vmcnt(6)
	ds_write2_b32 v0, v88, v89 offset1:66
	s_waitcnt vmcnt(4)
	ds_write2_b32 v0, v90, v91 offset0:132 offset1:198
	s_waitcnt vmcnt(2)
	ds_write2_b32 v48, v92, v93 offset0:8 offset1:74
	s_waitcnt vmcnt(0)
	ds_write2_b32 v48, v94, v95 offset0:140 offset1:206
	v_add_u32_e32 v0, 0x840, v0
	s_cmp_lg_u32 s22, 0x2c0000
	s_waitcnt lgkmcnt(0)
	ds_read2_b32 v[18:19], v33 offset0:33 offset1:41
	ds_read2_b32 v[20:21], v33 offset1:8
	ds_read2_b32 v[22:23], v33 offset0:66 offset1:74
	ds_read2_b32 v[24:25], v33 offset0:99 offset1:107
	ds_read2_b32 v[26:27], v33 offset0:132 offset1:140
	ds_read2_b32 v[28:29], v33 offset0:165 offset1:173
	ds_read2_b32 v[48:49], v33 offset0:198 offset1:206
	ds_read2_b32 v[50:51], v33 offset0:231 offset1:239
	v_or_b32_e32 v54, s6, v157
	s_ashr_i32 s21, s20, 31
	v_ashrrev_i32_e32 v55, 31, v54
	v_lshl_add_u64 v[52:53], s[20:21], 1, v[10:11]
	v_lshlrev_b64 v[54:55], 12, v[54:55]
	s_waitcnt lgkmcnt(6)
	v_cvt_pk_bf16_f32 v14, v20, v18
	s_waitcnt lgkmcnt(4)
	v_cvt_pk_bf16_f32 v15, v22, v24
	s_waitcnt lgkmcnt(2)
	v_cvt_pk_bf16_f32 v16, v26, v28
	s_waitcnt lgkmcnt(0)
	v_cvt_pk_bf16_f32 v17, v48, v50
	v_lshl_add_u64 v[54:55], v[52:53], 0, v[54:55]
	v_or_b32_e32 v18, s6, v34
	global_store_dwordx4 v[54:55], v[14:17], off
	s_mov_b64 s[20:21], 0
	s_nop 0
	v_cvt_pk_bf16_f32 v14, v21, v19
	v_ashrrev_i32_e32 v19, 31, v18
	v_cvt_pk_bf16_f32 v15, v23, v25
	v_cvt_pk_bf16_f32 v16, v27, v29
	v_cvt_pk_bf16_f32 v17, v49, v51
	v_lshlrev_b64 v[18:19], 12, v[18:19]
	ds_read2_b32 v[20:21], v33 offset0:49 offset1:57
	ds_read2_b32 v[22:23], v33 offset0:16 offset1:24
	ds_read2_b32 v[24:25], v33 offset0:82 offset1:90
	ds_read2_b32 v[26:27], v33 offset0:115 offset1:123
	ds_read2_b32 v[28:29], v33 offset0:148 offset1:156
	ds_read2_b32 v[48:49], v33 offset0:181 offset1:189
	ds_read2_b32 v[50:51], v33 offset0:214 offset1:222
	ds_read2_b32 v[54:55], v33 offset0:247 offset1:255
	v_lshl_add_u64 v[18:19], v[52:53], 0, v[18:19]
	global_store_dwordx4 v[18:19], v[14:17], off
	v_or_b32_e32 v18, s6, v35
	v_ashrrev_i32_e32 v19, 31, v18
	v_lshlrev_b64 v[18:19], 12, v[18:19]
	s_waitcnt lgkmcnt(6)
	v_cvt_pk_bf16_f32 v14, v22, v20
	s_waitcnt lgkmcnt(4)
	v_cvt_pk_bf16_f32 v15, v24, v26
	s_waitcnt lgkmcnt(2)
	v_cvt_pk_bf16_f32 v16, v28, v48
	s_waitcnt lgkmcnt(0)
	v_cvt_pk_bf16_f32 v17, v50, v54
	v_lshl_add_u64 v[18:19], v[52:53], 0, v[18:19]
	global_store_dwordx4 v[18:19], v[14:17], off
	v_or_b32_e32 v18, s6, v36
	v_ashrrev_i32_e32 v19, 31, v18
	v_lshlrev_b64 v[18:19], 12, v[18:19]
	v_cvt_pk_bf16_f32 v14, v23, v21
	v_cvt_pk_bf16_f32 v15, v25, v27
	v_cvt_pk_bf16_f32 v16, v29, v49
	v_cvt_pk_bf16_f32 v17, v51, v55
	v_lshl_add_u64 v[18:19], v[52:53], 0, v[18:19]
	global_store_dwordx4 v[18:19], v[14:17], off
	s_waitcnt lgkmcnt(0)

; __device__ __forceinline__ void transpose_item(const float* W, int K, int N, bf16_t* WT, int dst0, int src0, int mode, int nblk, LAS float* scr, int item, int lane) {
;     ...
;     const int sc = srccol(mode, n0 + (lane & 31), src0);
; #pragma unroll 8
;     for (int i = 0; i < 32; ++i) { const int kk = 2 * i + (lane >> 5); scr[kk * 33 + (lane & 31)] = __builtin_nontemporal_load(W + (size_t)(k0 + kk) * N + sc); }
.LBB0_351:
	v_add_u32_e32 v18, s7, v0
	v_ashrrev_i32_e32 v19, 31, v18
	v_add_u32_e32 v20, 2, v18
	v_add_u32_e32 v22, 4, v18
	v_add_u32_e32 v24, 6, v18
	v_add_u32_e32 v26, 8, v18
	v_add_u32_e32 v28, 10, v18
	v_add_u32_e32 v48, 12, v18
	v_add_u32_e32 v50, 14, v18
	v_lshlrev_b64 v[18:19], 13, v[18:19]
	v_ashrrev_i32_e32 v21, 31, v20
	v_ashrrev_i32_e32 v23, 31, v22
	v_ashrrev_i32_e32 v25, 31, v24
	v_ashrrev_i32_e32 v27, 31, v26
	v_ashrrev_i32_e32 v29, 31, v28
	v_ashrrev_i32_e32 v49, 31, v48
	v_ashrrev_i32_e32 v51, 31, v50
	v_lshl_add_u64 v[18:19], v[14:15], 0, v[18:19]
	v_lshlrev_b64 v[20:21], 13, v[20:21]
	v_lshlrev_b64 v[22:23], 13, v[22:23]
	v_lshlrev_b64 v[24:25], 13, v[24:25]
	v_lshlrev_b64 v[26:27], 13, v[26:27]
	v_lshlrev_b64 v[28:29], 13, v[28:29]
	v_lshlrev_b64 v[48:49], 13, v[48:49]
	v_lshlrev_b64 v[50:51], 13, v[50:51]
	v_lshl_add_u64 v[20:21], v[14:15], 0, v[20:21]
	v_lshl_add_u64 v[22:23], v[14:15], 0, v[22:23]
	v_lshl_add_u64 v[24:25], v[14:15], 0, v[24:25]
	v_lshl_add_u64 v[26:27], v[14:15], 0, v[26:27]
	v_lshl_add_u64 v[28:29], v[14:15], 0, v[28:29]
	v_lshl_add_u64 v[48:49], v[14:15], 0, v[48:49]
	v_lshl_add_u64 v[50:51], v[14:15], 0, v[50:51]
	global_load_dword v64, v[18:19], off nt
	global_load_dword v65, v[20:21], off nt
	global_load_dword v66, v[22:23], off nt
	global_load_dword v67, v[24:25], off nt
	global_load_dword v68, v[26:27], off nt
	global_load_dword v69, v[28:29], off nt
	global_load_dword v70, v[48:49], off nt
	global_load_dword v71, v[50:51], off nt
	s_add_i32 s7, s7, 16
	v_add_u32_e32 v18, s7, v0
	v_ashrrev_i32_e32 v19, 31, v18
	v_add_u32_e32 v20, 2, v18
	v_add_u32_e32 v22, 4, v18
	v_add_u32_e32 v24, 6, v18
	v_add_u32_e32 v26, 8, v18
	v_add_u32_e32 v28, 10, v18
	v_add_u32_e32 v48, 12, v18
	v_add_u32_e32 v50, 14, v18
	v_lshlrev_b64 v[18:19], 13, v[18:19]
	v_ashrrev_i32_e32 v21, 31, v20
	v_ashrrev_i32_e32 v23, 31, v22
	v_ashrrev_i32_e32 v25, 31, v24
	v_ashrrev_i32_e32 v27, 31, v26
	v_ashrrev_i32_e32 v29, 31, v28
	v_ashrrev_i32_e32 v49, 31, v48
	v_ashrrev_i32_e32 v51, 31, v50
	v_lshl_add_u64 v[18:19], v[14:15], 0, v[18:19]
	v_lshlrev_b64 v[20:21], 13, v[20:21]
	v_lshlrev_b64 v[22:23], 13, v[22:23]
	v_lshlrev_b64 v[24:25], 13, v[24:25]
	v_lshlrev_b64 v[26:27], 13, v[26:27]
	v_lshlrev_b64 v[28:29], 13, v[28:29]
	v_lshlrev_b64 v[48:49], 13, v[48:49]
	v_lshlrev_b64 v[50:51], 13, v[50:51]
	v_lshl_add_u64 v[20:21], v[14:15], 0, v[20:21]
	v_lshl_add_u64 v[22:23], v[14:15], 0, v[22:23]
	v_lshl_add_u64 v[24:25], v[14:15], 0, v[24:25]
	v_lshl_add_u64 v[26:27], v[14:15], 0, v[26:27]
	v_lshl_add_u64 v[28:29], v[14:15], 0, v[28:29]
	v_lshl_add_u64 v[48:49], v[14:15], 0, v[48:49]
	v_lshl_add_u64 v[50:51], v[14:15], 0, v[50:51]
	global_load_dword v72, v[18:19], off nt
	global_load_dword v73, v[20:21], off nt
	global_load_dword v74, v[22:23], off nt
	global_load_dword v75, v[24:25], off nt
	global_load_dword v76, v[26:27], off nt
	global_load_dword v77, v[28:29], off nt
	global_load_dword v78, v[48:49], off nt
	global_load_dword v79, v[50:51], off nt
	s_add_i32 s7, s7, 16
	v_add_u32_e32 v18, s7, v0
	v_ashrrev_i32_e32 v19, 31, v18
	v_add_u32_e32 v20, 2, v18
	v_add_u32_e32 v22, 4, v18
	v_add_u32_e32 v24, 6, v18
	v_add_u32_e32 v26, 8, v18
	v_add_u32_e32 v28, 10, v18
	v_add_u32_e32 v48, 12, v18
	v_add_u32_e32 v50, 14, v18
	v_lshlrev_b64 v[18:19], 13, v[18:19]
	v_ashrrev_i32_e32 v21, 31, v20
	v_ashrrev_i32_e32 v23, 31, v22
	v_ashrrev_i32_e32 v25, 31, v24
	v_ashrrev_i32_e32 v27, 31, v26
	v_ashrrev_i32_e32 v29, 31, v28
	v_ashrrev_i32_e32 v49, 31, v48
	v_ashrrev_i32_e32 v51, 31, v50
	v_lshl_add_u64 v[18:19], v[14:15], 0, v[18:19]
	v_lshlrev_b64 v[20:21], 13, v[20:21]
	v_lshlrev_b64 v[22:23], 13, v[22:23]
	v_lshlrev_b64 v[24:25], 13, v[24:25]
	v_lshlrev_b64 v[26:27], 13, v[26:27]
	v_lshlrev_b64 v[28:29], 13, v[28:29]
	v_lshlrev_b64 v[48:49], 13, v[48:49]
	v_lshlrev_b64 v[50:51], 13, v[50:51]
	v_lshl_add_u64 v[20:21], v[14:15], 0, v[20:21]
	v_lshl_add_u64 v[22:23], v[14:15], 0, v[22:23]
	v_lshl_add_u64 v[24:25], v[14:15], 0, v[24:25]
	v_lshl_add_u64 v[26:27], v[14:15], 0, v[26:27]
	v_lshl_add_u64 v[28:29], v[14:15], 0, v[28:29]
	v_lshl_add_u64 v[48:49], v[14:15], 0, v[48:49]
	v_lshl_add_u64 v[50:51], v[14:15], 0, v[50:51]
	global_load_dword v80, v[18:19], off nt
	global_load_dword v81, v[20:21], off nt
	global_load_dword v82, v[22:23], off nt
	global_load_dword v83, v[24:25], off nt
	global_load_dword v84, v[26:27], off nt
	global_load_dword v85, v[28:29], off nt
	global_load_dword v86, v[48:49], off nt
	global_load_dword v87, v[50:51], off nt
	s_add_i32 s7, s7, 16
	v_add_u32_e32 v18, s7, v0
	v_ashrrev_i32_e32 v19, 31, v18
	v_add_u32_e32 v20, 2, v18
	v_add_u32_e32 v22, 4, v18
	v_add_u32_e32 v24, 6, v18
	v_add_u32_e32 v26, 8, v18
	v_add_u32_e32 v28, 10, v18
	v_add_u32_e32 v48, 12, v18
	v_add_u32_e32 v50, 14, v18
	v_lshlrev_b64 v[18:19], 13, v[18:19]
	v_ashrrev_i32_e32 v21, 31, v20
	v_ashrrev_i32_e32 v23, 31, v22
	v_ashrrev_i32_e32 v25, 31, v24
	v_ashrrev_i32_e32 v27, 31, v26
	v_ashrrev_i32_e32 v29, 31, v28
	v_ashrrev_i32_e32 v49, 31, v48
	v_ashrrev_i32_e32 v51, 31, v50
	v_lshl_add_u64 v[18:19], v[14:15], 0, v[18:19]
	v_lshlrev_b64 v[20:21], 13, v[20:21]
	v_lshlrev_b64 v[22:23], 13, v[22:23]
	v_lshlrev_b64 v[24:25], 13, v[24:25]
	v_lshlrev_b64 v[26:27], 13, v[26:27]
	v_lshlrev_b64 v[28:29], 13, v[28:29]
	v_lshlrev_b64 v[48:49], 13, v[48:49]
	v_lshlrev_b64 v[50:51], 13, v[50:51]
	v_lshl_add_u64 v[20:21], v[14:15], 0, v[20:21]
	v_lshl_add_u64 v[22:23], v[14:15], 0, v[22:23]
	v_lshl_add_u64 v[24:25], v[14:15], 0, v[24:25]
	v_lshl_add_u64 v[26:27], v[14:15], 0, v[26:27]
	v_lshl_add_u64 v[28:29], v[14:15], 0, v[28:29]
	v_lshl_add_u64 v[48:49], v[14:15], 0, v[48:49]
	v_lshl_add_u64 v[50:51], v[14:15], 0, v[50:51]
	global_load_dword v88, v[18:19], off nt
	global_load_dword v89, v[20:21], off nt
	global_load_dword v90, v[22:23], off nt
	global_load_dword v91, v[24:25], off nt
	global_load_dword v92, v[26:27], off nt
	global_load_dword v93, v[28:29], off nt
	global_load_dword v94, v[48:49], off nt
	global_load_dword v95, v[50:51], off nt
	s_add_i32 s7, s7, 16
	v_add_u32_e32 v18, 0x400, v16
	s_waitcnt vmcnt(30)
; #define LAS __attribute__((address_space(3)))
; __device__ __forceinline__ unsigned pk2(float lo, float hi) { return pg8::cvt_pk_bf16(lo, hi); }
; __device__ __forceinline__ void transpose_item(const float* W, int K, int N, bf16_t* WT, int dst0, int src0, int mode, int nblk, LAS float* scr, int item, int lane) {
;     ...
;     for (int i = 0; i < 32; ++i) { const int kk = 2 * i + (lane >> 5); scr[kk * 33 + (lane & 31)] = __builtin_nontemporal_load(W + (size_t)(k0 + kk) * N + sc); }
;     asm volatile("s_waitcnt lgkmcnt(0)" ::: "memory");
;     const int c = lane & 7;
; #pragma unroll
;     for (int j = 0; j < 4; ++j) { const int n = (lane >> 3) + 8 * j; const LAS float* s = scr + (8 * c) * 33 + n;
;         u32x4 o; o.x = pk2(s[0 * 33], s[1 * 33]); o.y = pk2(s[2 * 33], s[3 * 33]); o.z = pk2(s[4 * 33], s[5 * 33]); o.w = pk2(s[6 * 33], s[7 * 33]);
;         *(u32x4*)(WT + (size_t)(dst0 + n0 + n) * K + k0 + 8 * c) = o; }
;     asm volatile("s_waitcnt lgkmcnt(0)" ::: "memory");
	ds_write2_b32 v16, v64, v65 offset1:66
	s_waitcnt vmcnt(28)
	ds_write2_b32 v16, v66, v67 offset0:132 offset1:198
	s_waitcnt vmcnt(26)
	ds_write2_b32 v18, v68, v69 offset0:8 offset1:74
	s_waitcnt vmcnt(24)
	ds_write2_b32 v18, v70, v71 offset0:140 offset1:206
	v_add_u32_e32 v16, 0x840, v16
	v_add_u32_e32 v18, 0x400, v16
	s_waitcnt vmcnt(22)
	ds_write2_b32 v16, v72, v73 offset1:66
	s_waitcnt vmcnt(20)
	ds_write2_b32 v16, v74, v75 offset0:132 offset1:198
	s_waitcnt vmcnt(18)
	ds_write2_b32 v18, v76, v77 offset0:8 offset1:74
	s_waitcnt vmcnt(16)
	ds_write2_b32 v18, v78, v79 offset0:140 offset1:206
	v_add_u32_e32 v16, 0x840, v16
	v_add_u32_e32 v18, 0x400, v16
	s_waitcnt vmcnt(14)
	ds_write2_b32 v16, v80, v81 offset1:66
	s_waitcnt vmcnt(12)
	ds_write2_b32 v16, v82, v83 offset0:132 offset1:198
	s_waitcnt vmcnt(10)
	ds_write2_b32 v18, v84, v85 offset0:8 offset1:74
	s_waitcnt vmcnt(8)
	ds_write2_b32 v18, v86, v87 offset0:140 offset1:206
	v_add_u32_e32 v16, 0x840, v16
	v_add_u32_e32 v18, 0x400, v16
	s_waitcnt vmcnt(6)
	ds_write2_b32 v16, v88, v89 offset1:66
	s_waitcnt vmcnt(4)
	ds_write2_b32 v16, v90, v91 offset0:132 offset1:198
	s_waitcnt vmcnt(2)
	ds_write2_b32 v18, v92, v93 offset0:8 offset1:74
	s_waitcnt vmcnt(0)
	ds_write2_b32 v18, v94, v95 offset0:140 offset1:206
	v_add_u32_e32 v16, 0x840, v16
	s_cmp_lg_u32 s7, 64
	s_waitcnt lgkmcnt(0)
	ds_read2_b32 v[18:19], v33 offset0:33 offset1:41
	ds_read2_b32 v[20:21], v33 offset1:8
	ds_read2_b32 v[22:23], v33 offset0:66 offset1:74
	ds_read2_b32 v[24:25], v33 offset0:99 offset1:107
	ds_read2_b32 v[26:27], v33 offset0:132 offset1:140
	ds_read2_b32 v[28:29], v33 offset0:165 offset1:173
	ds_read2_b32 v[48:49], v33 offset0:198 offset1:206
	ds_read2_b32 v[50:51], v33 offset0:231 offset1:239
	v_or_b32_e32 v0, s6, v157
	s_ashr_i32 s19, s18, 31
	v_mul_lo_u32 v54, v0, s28
	v_lshl_add_u64 v[52:53], s[18:19], 1, v[12:13]
	v_ashrrev_i32_e32 v55, 31, v54
	s_waitcnt lgkmcnt(6)
	v_cvt_pk_bf16_f32 v14, v20, v18
	s_waitcnt lgkmcnt(4)
	v_cvt_pk_bf16_f32 v15, v22, v24
	s_waitcnt lgkmcnt(2)
	v_cvt_pk_bf16_f32 v16, v26, v28
	s_waitcnt lgkmcnt(0)
	v_cvt_pk_bf16_f32 v17, v48, v50
	v_lshl_add_u64 v[54:55], v[54:55], 1, v[52:53]
	global_store_dwordx4 v[54:55], v[14:17], off
	v_or_b32_e32 v0, s6, v34
	v_mul_lo_u32 v18, v0, s28
	v_cvt_pk_bf16_f32 v14, v21, v19
	v_cvt_pk_bf16_f32 v15, v23, v25
	v_cvt_pk_bf16_f32 v16, v27, v29
	v_cvt_pk_bf16_f32 v17, v49, v51
	ds_read2_b32 v[20:21], v33 offset0:49 offset1:57
	ds_read2_b32 v[22:23], v33 offset0:16 offset1:24
	ds_read2_b32 v[24:25], v33 offset0:82 offset1:90
	ds_read2_b32 v[26:27], v33 offset0:115 offset1:123
	ds_read2_b32 v[28:29], v33 offset0:148 offset1:156
	ds_read2_b32 v[48:49], v33 offset0:181 offset1:189
	ds_read2_b32 v[50:51], v33 offset0:214 offset1:222
	ds_read2_b32 v[54:55], v33 offset0:247 offset1:255
	v_ashrrev_i32_e32 v19, 31, v18
	v_lshl_add_u64 v[18:19], v[18:19], 1, v[52:53]
	v_or_b32_e32 v0, s6, v35
	global_store_dwordx4 v[18:19], v[14:17], off
	v_mul_lo_u32 v18, v0, s28
	v_ashrrev_i32_e32 v19, 31, v18
	s_waitcnt lgkmcnt(6)
	v_cvt_pk_bf16_f32 v14, v22, v20
	s_waitcnt lgkmcnt(4)
	v_cvt_pk_bf16_f32 v15, v24, v26
	s_waitcnt lgkmcnt(2)
	v_cvt_pk_bf16_f32 v16, v28, v48
	s_waitcnt lgkmcnt(0)
	v_cvt_pk_bf16_f32 v17, v50, v54
	v_lshl_add_u64 v[18:19], v[18:19], 1, v[52:53]
	v_or_b32_e32 v0, s6, v36
	global_store_dwordx4 v[18:19], v[14:17], off
	v_mul_lo_u32 v18, v0, s28
	v_ashrrev_i32_e32 v19, 31, v18
	v_cvt_pk_bf16_f32 v14, v23, v21
	v_cvt_pk_bf16_f32 v15, v25, v27
	v_cvt_pk_bf16_f32 v16, v29, v49
	v_cvt_pk_bf16_f32 v17, v51, v55
	v_lshl_add_u64 v[18:19], v[18:19], 1, v[52:53]
	global_store_dwordx4 v[18:19], v[14:17], off
	s_waitcnt lgkmcnt(0)
	s_branch .LBB0_300
